# v36 with the two hot attention tile loops aligned to 64 bytes
# baseline (speedup 1.0000x reference)
; __device__ __forceinline__ float bflo(unsigned w) { return __uint_as_float(w << 16); }
; __device__ __forceinline__ float bfhi(unsigned w) { return __uint_as_float(w & 0xffff0000u); }
; __device__ __forceinline__ float pairsum(float v) { auto rr = __builtin_amdgcn_permlane32_swap(__float_as_uint(v), __float_as_uint(v), false, false); return __uint_as_float(rr[0]) + __uint_as_float(rr[1]); }
;     ...
;         const bf16_t* src = U.q + (size_t)(32 * qb + r32) * QP + 8 * hi;
;         u32x4 raw[ND];
; #pragma unroll
;         for (int d0 = 0; d0 < ND; ++d0) raw[d0] = *(const u32x4*)(src + 16 * d0);
;         int pos = U.tq0 + 32 * qb + r32; asm volatile("" : "+v"(pos));
;         if constexpr (MODE == 1) {
; #pragma unroll
;             for (int d0 = 0; d0 < ND; ++d0) qf[qb][d0] = __builtin_bit_cast(bf16x8, raw[d0]);
;         } else if constexpr (MODE == 0) {
;             float v[4][8]; float ss = 0.f;
; #pragma unroll
;             for (int d0 = 0; d0 < 4; ++d0)
; #pragma unroll
;                 for (int j = 0; j < 4; ++j) { const unsigned w = raw[d0][j]; v[d0][2 * j] = bflo(w); v[d0][2 * j + 1] = bfhi(w); ss += v[d0][2 * j] * v[d0][2 * j] + v[d0][2 * j + 1] * v[d0][2 * j + 1]; }
;             ss = pairsum(ss);
;             const float rstd = rsqrtf(ss * (1.0f / 64.0f) + EPSN) * C2_64;
; #pragma unroll
;             for (int d0 = 0; d0 < 4; ++d0)
; #pragma unroll
;                 for (int j = 0; j < 8; ++j) v[d0][j] *= rstd * U.gain[16 * d0 + 8 * hi + j];
;             const int row = pos >> 6, col = pos & 63;
; #pragma unroll
;             for (int j = 0; j < 8; ++j) {
;                 __builtin_amdgcn_sched_barrier(0);
;                 const float fi = hi ? invf_c(8 + j) : invf_c(j); float c, s;
;                 rope_cs(row, fi, c, s); { const float x1 = v[0][j], x2 = v[1][j]; v[0][j] = x1 * c - x2 * s; v[1][j] = x2 * c + x1 * s; }
;                 rope_cs(col, fi, c, s); { const float x1 = v[2][j], x2 = v[3][j]; v[2][j] = x1 * c - x2 * s; v[3][j] = x2 * c + x1 * s; }
;             }
.LBB0_436:
	s_add_u32 s46, s12, s46
	s_addc_u32 s47, s13, s47
	s_add_i32 s87, s87, s86
	s_add_u32 s4, s53, s88
	s_addc_u32 s5, s54, s87
	s_lshl_b32 s6, s85, 1
	s_add_u32 s10, s4, s6
	s_addc_u32 s11, s5, 0
	s_lshl_b64 s[6:7], s[44:45], 22
	s_add_u32 s4, s55, s6
	s_addc_u32 s5, s56, s7
	s_lshl_b32 s33, s84, 1
	s_add_u32 s4, s4, s33
	s_load_dwordx2 s[8:9], s[24:25], 0x30
	s_addc_u32 s5, s5, 0
	s_add_u32 s6, s57, s6
	s_addc_u32 s7, s58, s7
	s_lshl_b32 s33, s83, 1
	v_mbcnt_lo_u32_b32 v229, -1, 0
	v_mbcnt_hi_u32_b32 v229, -1, v229
	s_add_u32 s6, s6, s33
	v_lshrrev_b32_e32 v0, 2, v229
	v_and_b32_e32 v228, 63, v229
	v_and_b32_e32 v227, 31, v229
	v_and_b32_e32 v2, 8, v0
	s_addc_u32 s7, s7, 0
	v_cmp_gt_u32_e32 vcc, 32, v228
	v_mul_u32_u24_e32 v0, 0x600, v227
	v_lshlrev_b32_e32 v168, 1, v0
	v_lshl_add_u64 v[0:1], s[10:11], 0, v[168:169]
	v_lshlrev_b32_e32 v168, 1, v2
	v_lshl_add_u64 v[0:1], v[0:1], 0, v[168:169]
	v_or_b32_e32 v32, s82, v227
	global_load_dwordx4 v[20:23], v[0:1], off
	global_load_dwordx4 v[16:19], v[0:1], off offset:32
	global_load_dwordx4 v[28:31], v[0:1], off offset:64
	global_load_dwordx4 v[24:27], v[0:1], off offset:96
	v_cndmask_b32_e64 v93, v206, 1.0, vcc
	v_ashrrev_i32_e32 v33, 6, v32
	v_cvt_f32_i32_e32 v33, v33
	v_and_b32_e32 v32, 63, v32
	v_cvt_f32_ubyte0_e32 v32, v32
	v_cndmask_b32_e32 v95, v207, v208, vcc
	v_mul_f32_e32 v34, v93, v33
	v_mul_f32_e32 v35, 0.15915494, v34
	v_rndne_f32_e32 v35, v35
	v_fmac_f32_e32 v34, 0xc0c90fdb, v35
	v_fmac_f32_e32 v34, 0x343bbd2e, v35
	v_mul_f32_e32 v34, 0.15915494, v34
	v_sin_f32_e32 v74, v34
	v_cos_f32_e32 v76, v34
	v_mul_f32_e32 v34, v93, v32
	v_mul_f32_e32 v35, 0.15915494, v34
	v_rndne_f32_e32 v35, v35
	v_fmac_f32_e32 v34, 0xc0c90fdb, v35
	v_fmac_f32_e32 v34, 0x343bbd2e, v35
	v_mul_f32_e32 v34, 0.15915494, v34
	v_sin_f32_e32 v78, v34
	v_cos_f32_e32 v80, v34
	v_mul_f32_e32 v34, v95, v33
	v_mul_f32_e32 v35, 0.15915494, v34
	v_rndne_f32_e32 v35, v35
	v_fmac_f32_e32 v34, 0xc0c90fdb, v35
	v_fmac_f32_e32 v34, 0x343bbd2e, v35
	v_mul_f32_e32 v34, 0.15915494, v34
	v_sin_f32_e32 v75, v34
	v_cos_f32_e32 v77, v34
	v_mul_f32_e32 v34, v95, v32
	s_movk_i32 s33, 0x7c
	v_mul_f32_e32 v35, 0.15915494, v34
	v_bitop3_b32 v73, v229, s33, v203 bitop3:0xc8
	s_movk_i32 s33, 0xbc
	v_rndne_f32_e32 v35, v35
	v_lshlrev_b32_e32 v61, 2, v2
	v_bitop3_b32 v69, v229, 60, 28 bitop3:0xc8
	v_bitop3_b32 v92, v229, s33, v204 bitop3:0xc8
	s_movk_i32 s33, 0xfc
	v_fmac_f32_e32 v34, 0xc0c90fdb, v35
	s_waitcnt lgkmcnt(0)
	global_load_dwordx3 v[56:58], v61, s[8:9] offset:16
	global_load_dwordx4 v[12:15], v61, s[8:9]
	global_load_dwordx3 v[52:54], v61, s[8:9] offset:80
	global_load_dwordx4 v[8:11], v61, s[8:9] offset:64
	global_load_dwordx3 v[48:50], v61, s[8:9] offset:144
	global_load_dwordx4 v[4:7], v61, s[8:9] offset:128
	global_load_dwordx3 v[44:46], v61, s[8:9] offset:208
	global_load_dwordx4 v[0:3], v61, s[8:9] offset:192
	v_bitop3_b32 v94, v229, s33, v205 bitop3:0xc8
	global_load_dword v83, v69, s[8:9]
	global_load_dword v55, v73, s[8:9]
	global_load_dword v51, v92, s[8:9]
	global_load_dword v47, v94, s[8:9]
	v_fmac_f32_e32 v34, 0x343bbd2e, v35
	v_mul_f32_e32 v34, 0.15915494, v34
	v_cndmask_b32_e32 v105, v209, v210, vcc
	v_sin_f32_e32 v79, v34
	v_cos_f32_e32 v81, v34
	v_mul_f32_e32 v34, v105, v33
	v_mul_f32_e32 v35, 0.15915494, v34
	v_rndne_f32_e32 v35, v35
	v_fmac_f32_e32 v34, 0xc0c90fdb, v35
	v_fmac_f32_e32 v34, 0x343bbd2e, v35
	v_mul_f32_e32 v34, 0.15915494, v34
	v_sin_f32_e32 v84, v34
	v_cos_f32_e32 v86, v34
	v_mul_f32_e32 v34, v105, v32
	v_mul_f32_e32 v35, 0.15915494, v34
	v_rndne_f32_e32 v35, v35
	v_fmac_f32_e32 v34, 0xc0c90fdb, v35
	v_fmac_f32_e32 v34, 0x343bbd2e, v35
	v_mul_f32_e32 v34, 0.15915494, v34
	v_cndmask_b32_e32 v107, v211, v218, vcc
	v_sin_f32_e32 v88, v34
	v_cos_f32_e32 v90, v34
	v_mul_f32_e32 v34, v107, v33
	v_mul_f32_e32 v35, 0.15915494, v34
	v_rndne_f32_e32 v35, v35
	v_fmac_f32_e32 v34, 0xc0c90fdb, v35
	v_fmac_f32_e32 v34, 0x343bbd2e, v35
	v_mul_f32_e32 v34, 0.15915494, v34
	v_sin_f32_e32 v85, v34
	v_cos_f32_e32 v87, v34
	v_mul_f32_e32 v34, v107, v32
	v_mul_f32_e32 v35, 0.15915494, v34
	v_rndne_f32_e32 v35, v35
	v_fmac_f32_e32 v34, 0xc0c90fdb, v35
	v_fmac_f32_e32 v34, 0x343bbd2e, v35
	v_mul_f32_e32 v34, 0.15915494, v34
	s_waitcnt vmcnt(17)
	v_cndmask_b32_e32 v132, v219, v220, vcc
	v_sin_f32_e32 v89, v34
	v_cos_f32_e32 v91, v34
	v_mul_f32_e32 v34, v132, v33
	v_mul_f32_e32 v35, 0.15915494, v34
	v_rndne_f32_e32 v35, v35
	v_fmac_f32_e32 v34, 0xc0c90fdb, v35
	v_fmac_f32_e32 v34, 0x343bbd2e, v35
	v_mul_f32_e32 v34, 0.15915494, v34
	v_sin_f32_e32 v96, v34
	v_cos_f32_e32 v98, v34
	v_mul_f32_e32 v34, v132, v32
	v_mul_f32_e32 v35, 0.15915494, v34
	v_rndne_f32_e32 v35, v35
	v_fmac_f32_e32 v34, 0xc0c90fdb, v35
	v_fmac_f32_e32 v34, 0x343bbd2e, v35
	v_mul_f32_e32 v34, 0.15915494, v34
	v_cndmask_b32_e32 v134, v221, v222, vcc
	v_sin_f32_e32 v100, v34
	v_cos_f32_e32 v102, v34
	v_mul_f32_e32 v34, v134, v33
	v_mul_f32_e32 v35, 0.15915494, v34
	v_rndne_f32_e32 v35, v35
	v_fmac_f32_e32 v34, 0xc0c90fdb, v35
	v_fmac_f32_e32 v34, 0x343bbd2e, v35
	v_mul_f32_e32 v34, 0.15915494, v34
	v_sin_f32_e32 v97, v34
	v_cos_f32_e32 v99, v34
	v_mul_f32_e32 v34, v134, v32
	v_mul_f32_e32 v35, 0.15915494, v34
	v_rndne_f32_e32 v35, v35
	v_fmac_f32_e32 v34, 0xc0c90fdb, v35
	v_fmac_f32_e32 v34, 0x343bbd2e, v35
	v_mul_f32_e32 v34, 0.15915494, v34
	v_cndmask_b32_e32 v104, v223, v224, vcc
	v_sin_f32_e32 v101, v34
	v_cos_f32_e32 v103, v34
	v_mul_f32_e32 v34, v104, v33
	v_mul_f32_e32 v35, 0.15915494, v34
	v_rndne_f32_e32 v35, v35
	v_fmac_f32_e32 v34, 0xc0c90fdb, v35
	v_fmac_f32_e32 v34, 0x343bbd2e, v35
	v_mul_f32_e32 v34, 0.15915494, v34
	v_sin_f32_e32 v108, v34
	v_cos_f32_e32 v110, v34
	v_mul_f32_e32 v34, v104, v32
	v_mul_f32_e32 v35, 0.15915494, v34
	v_rndne_f32_e32 v35, v35
	v_fmac_f32_e32 v34, 0xc0c90fdb, v35
	v_fmac_f32_e32 v34, 0x343bbd2e, v35
	v_cndmask_b32_e32 v178, v225, v226, vcc
	v_mul_f32_e32 v34, 0.15915494, v34
	v_mul_f32_e32 v33, v178, v33
	s_waitcnt vmcnt(17)
; __device__ __forceinline__ float bflo(unsigned w) { return __uint_as_float(w << 16); }
; __device__ __forceinline__ float bfhi(unsigned w) { return __uint_as_float(w & 0xffff0000u); }
; __device__ __forceinline__ float pairsum(float v) { auto rr = __builtin_amdgcn_permlane32_swap(__float_as_uint(v), __float_as_uint(v), false, false); return __uint_as_float(rr[0]) + __uint_as_float(rr[1]); }
;     ...
;     for (int qb = 0; qb < 2; ++qb) {
;         __builtin_amdgcn_sched_barrier(0);
;         const bf16_t* src = U.q + (size_t)(32 * qb + r32) * QP + 8 * hi;
;         u32x4 raw[ND];
; #pragma unroll
;         for (int d0 = 0; d0 < ND; ++d0) raw[d0] = *(const u32x4*)(src + 16 * d0);
;         int pos = U.tq0 + 32 * qb + r32; asm volatile("" : "+v"(pos));
;         if constexpr (MODE == 1) {
; #pragma unroll
;             for (int d0 = 0; d0 < ND; ++d0) qf[qb][d0] = __builtin_bit_cast(bf16x8, raw[d0]);
;         } else if constexpr (MODE == 0) {
;             float v[4][8]; float ss = 0.f;
; #pragma unroll
;             for (int d0 = 0; d0 < 4; ++d0)
; #pragma unroll
;                 for (int j = 0; j < 4; ++j) { const unsigned w = raw[d0][j]; v[d0][2 * j] = bflo(w); v[d0][2 * j + 1] = bfhi(w); ss += v[d0][2 * j] * v[d0][2 * j] + v[d0][2 * j + 1] * v[d0][2 * j + 1]; }
;             ss = pairsum(ss);
;             const float rstd = rsqrtf(ss * (1.0f / 64.0f) + EPSN) * C2_64;
; #pragma unroll
;             for (int d0 = 0; d0 < 4; ++d0)
; #pragma unroll
;                 for (int j = 0; j < 8; ++j) v[d0][j] *= rstd * U.gain[16 * d0 + 8 * hi + j];
	v_sin_f32_e32 v112, v34
	v_cos_f32_e32 v114, v34
	v_mul_f32_e32 v34, 0.15915494, v33
	v_rndne_f32_e32 v34, v34
	v_fmac_f32_e32 v33, 0xc0c90fdb, v34
	v_fmac_f32_e32 v33, 0x343bbd2e, v34
	v_mul_f32_e32 v33, 0.15915494, v33
	v_mul_f32_e32 v32, v178, v32
	v_sin_f32_e32 v109, v33
	v_cos_f32_e32 v111, v33
	v_mul_f32_e32 v33, 0.15915494, v32
	v_rndne_f32_e32 v33, v33
	v_fmac_f32_e32 v32, 0xc0c90fdb, v33
	v_fmac_f32_e32 v32, 0x343bbd2e, v33
	v_mul_f32_e32 v32, 0.15915494, v32
	s_waitcnt vmcnt(13)
	v_and_b32_e32 v119, 0xffff0000, v31
	v_and_b32_e32 v121, 0xffff0000, v30
	v_sin_f32_e32 v113, v32
	v_cos_f32_e32 v115, v32
	v_lshlrev_b32_e32 v118, 16, v31
	v_lshlrev_b32_e32 v120, 16, v30
	v_mov_b32_e32 v32, v119
	v_mov_b32_e32 v33, v121
	s_waitcnt vmcnt(12)
	v_and_b32_e32 v117, 0xffff0000, v27
	v_mov_b32_e32 v30, v118
	v_mov_b32_e32 v31, v120
	v_pk_mul_f32 v[32:33], v[32:33], v[32:33]
	v_and_b32_e32 v123, 0xffff0000, v26
	v_lshlrev_b32_e32 v116, 16, v27
	v_pk_fma_f32 v[30:31], v[30:31], v[30:31], v[32:33]
	v_lshlrev_b32_e32 v122, 16, v26
	v_mov_b32_e32 v32, v117
	v_mov_b32_e32 v33, v123
	v_mov_b32_e32 v26, v116
	v_mov_b32_e32 v27, v122
	v_pk_mul_f32 v[32:33], v[32:33], v[32:33]
	v_and_b32_e32 v127, 0xffff0000, v29
	v_and_b32_e32 v129, 0xffff0000, v28
	v_pk_fma_f32 v[26:27], v[26:27], v[26:27], v[32:33]
	v_lshlrev_b32_e32 v126, 16, v29
	v_lshlrev_b32_e32 v128, 16, v28
	v_mov_b32_e32 v32, v127
	v_mov_b32_e32 v33, v129
	v_and_b32_e32 v125, 0xffff0000, v25
	v_mov_b32_e32 v28, v126
	v_mov_b32_e32 v29, v128
	v_pk_mul_f32 v[32:33], v[32:33], v[32:33]
	v_and_b32_e32 v131, 0xffff0000, v24
	v_and_b32_e32 v173, 0xffff0000, v21
	v_and_b32_e32 v177, 0xffff0000, v20
	v_lshlrev_b32_e32 v124, 16, v25
	v_pk_fma_f32 v[28:29], v[28:29], v[28:29], v[32:33]
	v_lshlrev_b32_e32 v130, 16, v24
	v_mov_b32_e32 v32, v125
	v_mov_b32_e32 v33, v131
	v_and_b32_e32 v165, 0xffff0000, v22
	v_lshlrev_b32_e32 v172, 16, v21
	v_mul_f32_e32 v36, v173, v173
	v_lshlrev_b32_e32 v176, 16, v20
	v_mul_f32_e32 v20, v177, v177
	v_mov_b32_e32 v24, v124
	v_mov_b32_e32 v25, v130
	v_pk_mul_f32 v[32:33], v[32:33], v[32:33]
	v_and_b32_e32 v161, 0xffff0000, v23
	v_and_b32_e32 v159, 0xffff0000, v19
	v_lshlrev_b32_e32 v164, 16, v22
	v_mul_f32_e32 v22, v165, v165
	v_and_b32_e32 v163, 0xffff0000, v18
	v_pk_fma_f32 v[36:37], v[172:173], v[172:173], v[36:37] op_sel_hi:[1,1,0]
	v_and_b32_e32 v167, 0xffff0000, v17
	v_pk_fma_f32 v[20:21], v[176:177], v[176:177], v[20:21] op_sel_hi:[1,1,0]
	v_and_b32_e32 v175, 0xffff0000, v16
	v_pk_fma_f32 v[24:25], v[24:25], v[24:25], v[32:33]
	v_lshlrev_b32_e32 v160, 16, v23
	v_mul_f32_e32 v32, v161, v161
	v_lshlrev_b32_e32 v158, 16, v19
	v_mul_f32_e32 v34, v159, v159
	v_pk_fma_f32 v[22:23], v[164:165], v[164:165], v[22:23] op_sel_hi:[1,1,0]
	v_lshlrev_b32_e32 v162, 16, v18
	v_mul_f32_e32 v18, v163, v163
	v_lshlrev_b32_e32 v166, 16, v17
	v_mul_f32_e32 v38, v167, v167
	v_lshlrev_b32_e32 v174, 16, v16
	v_mul_f32_e32 v16, v175, v175
	v_pk_add_f32 v[20:21], v[20:21], v[36:37]
	v_pk_fma_f32 v[32:33], v[160:161], v[160:161], v[32:33] op_sel_hi:[1,1,0]
	v_pk_fma_f32 v[34:35], v[158:159], v[158:159], v[34:35] op_sel_hi:[1,1,0]
	s_waitcnt vmcnt(11)
	v_mov_b32_e32 v82, v58
	v_pk_fma_f32 v[18:19], v[162:163], v[162:163], v[18:19] op_sel_hi:[1,1,0]
	v_pk_fma_f32 v[38:39], v[166:167], v[166:167], v[38:39] op_sel_hi:[1,1,0]
	v_pk_fma_f32 v[16:17], v[174:175], v[174:175], v[16:17] op_sel_hi:[1,1,0]
	v_pk_add_f32 v[20:21], v[22:23], v[20:21]
	s_nop 0
	v_pk_add_f32 v[20:21], v[32:33], v[20:21]
	s_nop 0
	v_pk_add_f32 v[16:17], v[16:17], v[20:21]
	s_nop 0
	v_pk_add_f32 v[16:17], v[38:39], v[16:17]
	s_nop 0
	v_pk_add_f32 v[16:17], v[18:19], v[16:17]
	s_nop 0
	v_pk_add_f32 v[16:17], v[34:35], v[16:17]
	s_nop 0
	v_pk_add_f32 v[16:17], v[28:29], v[16:17] op_sel:[1,0] op_sel_hi:[0,1]
	v_pk_add_f32 v[16:17], v[28:29], v[16:17]
	s_nop 0
	v_pk_add_f32 v[16:17], v[30:31], v[16:17] op_sel:[1,0] op_sel_hi:[0,1]
	v_pk_add_f32 v[16:17], v[30:31], v[16:17]
	s_nop 0
	v_pk_add_f32 v[16:17], v[24:25], v[16:17] op_sel:[1,0] op_sel_hi:[0,1]
	v_pk_add_f32 v[16:17], v[24:25], v[16:17]
	s_nop 0
	v_pk_add_f32 v[16:17], v[26:27], v[16:17] op_sel:[1,0] op_sel_hi:[0,1]
	v_pk_add_f32 v[192:193], v[26:27], v[16:17]
	s_nop 0
	v_mov_b32_e32 v65, v192
	s_nop 1
	v_permlane32_swap_b32_e32 v192, v65
	v_or_b32_e32 v18, 32, v228
	v_mul_u32_u24_e32 v16, 0x600, v18
	v_lshlrev_b32_e32 v16, 1, v16
	v_mov_b32_e32 v17, v169
	v_lshl_add_u64 v[16:17], s[10:11], 0, v[16:17]
	v_lshl_add_u64 v[16:17], v[16:17], 0, v[168:169]
	global_load_dwordx4 v[36:39], v[16:17], off
	global_load_dwordx4 v[32:35], v[16:17], off offset:32
	global_load_dwordx4 v[194:197], v[16:17], off offset:64
	global_load_dwordx4 v[40:43], v[16:17], off offset:96
	v_or_b32_e32 v106, s82, v18
	global_load_dwordx3 v[58:60], v61, s[8:9] offset:16
	global_load_dwordx4 v[16:19], v61, s[8:9]
	global_load_dwordx3 v[62:64], v61, s[8:9] offset:80
	global_load_dwordx4 v[20:23], v61, s[8:9] offset:64
	global_load_dwordx3 v[66:68], v61, s[8:9] offset:144
	global_load_dwordx4 v[24:27], v61, s[8:9] offset:128
	global_load_dwordx3 v[70:72], v61, s[8:9] offset:208
	global_load_dwordx4 v[28:31], v61, s[8:9] offset:192
	s_nop 0
	global_load_dword v69, v69, s[8:9]
	s_nop 0
	global_load_dword v61, v73, s[8:9]
	global_load_dword v133, v92, s[8:9]
	s_nop 0
	global_load_dword v73, v94, s[8:9]
	v_and_b32_e32 v92, 63, v106
	v_cvt_f32_ubyte0_e32 v168, v92
	v_mul_f32_e32 v92, v104, v168
	v_mul_f32_e32 v94, 0.15915494, v92
	v_rndne_f32_e32 v94, v94
	v_fmac_f32_e32 v92, 0xc0c90fdb, v94
	v_fmac_f32_e32 v92, 0x343bbd2e, v94
	v_ashrrev_i32_e32 v94, 6, v106
	v_mul_f32_e32 v135, v134, v168
; __device__ __forceinline__ float bflo(unsigned w) { return __uint_as_float(w << 16); }
; __device__ __forceinline__ float bfhi(unsigned w) { return __uint_as_float(w & 0xffff0000u); }
; __device__ __forceinline__ float pairsum(float v) { auto rr = __builtin_amdgcn_permlane32_swap(__float_as_uint(v), __float_as_uint(v), false, false); return __uint_as_float(rr[0]) + __uint_as_float(rr[1]); }
;     ...
;             for (int d0 = 0; d0 < 4; ++d0)
; #pragma unroll
;                 for (int j = 0; j < 4; ++j) { const unsigned w = raw[d0][j]; v[d0][2 * j] = bflo(w); v[d0][2 * j + 1] = bfhi(w); ss += v[d0][2 * j] * v[d0][2 * j] + v[d0][2 * j + 1] * v[d0][2 * j + 1]; }
;             ss = pairsum(ss);
;             const float rstd = rsqrtf(ss * (1.0f / 64.0f) + EPSN) * C2_64;
; #pragma unroll
;             for (int d0 = 0; d0 < 4; ++d0)
; #pragma unroll
;                 for (int j = 0; j < 8; ++j) v[d0][j] *= rstd * U.gain[16 * d0 + 8 * hi + j];
;             const int row = pos >> 6, col = pos & 63;
; #pragma unroll
;             for (int j = 0; j < 8; ++j) {
;                 __builtin_amdgcn_sched_barrier(0);
;                 const float fi = hi ? invf_c(8 + j) : invf_c(j); float c, s;
;                 rope_cs(row, fi, c, s); { const float x1 = v[0][j], x2 = v[1][j]; v[0][j] = x1 * c - x2 * s; v[1][j] = x2 * c + x1 * s; }
;                 rope_cs(col, fi, c, s); { const float x1 = v[2][j], x2 = v[3][j]; v[2][j] = x1 * c - x2 * s; v[3][j] = x2 * c + x1 * s; }
;             }
	v_cvt_f32_i32_e32 v179, v94
	v_mul_f32_e32 v136, 0.15915494, v135
	v_rndne_f32_e32 v136, v136
	v_fmac_f32_e32 v135, 0xc0c90fdb, v136
	v_fmac_f32_e32 v135, 0x343bbd2e, v136
	v_mul_f32_e32 v136, 0.15915494, v135
	v_mul_f32_e32 v134, v134, v179
	v_cos_f32_e32 v135, v136
	v_sin_f32_e32 v137, v136
	v_mul_f32_e32 v136, 0.15915494, v134
	v_rndne_f32_e32 v136, v136
	v_fmac_f32_e32 v134, 0xc0c90fdb, v136
	v_fmac_f32_e32 v134, 0x343bbd2e, v136
	v_mul_f32_e32 v134, 0.15915494, v134
	v_cos_f32_e32 v139, v134
	v_sin_f32_e32 v141, v134
	v_mul_f32_e32 v134, v132, v168
	v_mul_f32_e32 v132, v132, v179
	v_mul_f32_e32 v138, 0.15915494, v132
	v_rndne_f32_e32 v138, v138
	v_fmac_f32_e32 v132, 0xc0c90fdb, v138
	v_fmac_f32_e32 v132, 0x343bbd2e, v138
	v_mul_f32_e32 v132, 0.15915494, v132
	v_cos_f32_e32 v138, v132
	v_sin_f32_e32 v140, v132
	v_mul_f32_e32 v132, v107, v168
	v_mul_f32_e32 v142, 0.15915494, v132
	v_rndne_f32_e32 v142, v142
	v_fmac_f32_e32 v132, 0xc0c90fdb, v142
	v_fmac_f32_e32 v132, 0x343bbd2e, v142
	v_mul_f32_e32 v132, 0.15915494, v132
	v_mul_f32_e32 v107, v107, v179
	v_cos_f32_e32 v143, v132
	v_sin_f32_e32 v145, v132
	v_mul_f32_e32 v132, 0.15915494, v107
	v_rndne_f32_e32 v132, v132
	v_fmac_f32_e32 v107, 0xc0c90fdb, v132
	v_fmac_f32_e32 v107, 0x343bbd2e, v132
	v_mul_f32_e32 v107, 0.15915494, v107
	v_cos_f32_e32 v147, v107
	v_sin_f32_e32 v151, v107
	v_mul_f32_e32 v107, v105, v168
	v_mul_f32_e32 v132, 0.15915494, v107
	v_rndne_f32_e32 v132, v132
	v_fmac_f32_e32 v107, 0xc0c90fdb, v132
	v_fmac_f32_e32 v107, 0x343bbd2e, v132
	v_mul_f32_e32 v107, 0.15915494, v107
	v_mul_f32_e32 v105, v105, v179
	v_cos_f32_e32 v142, v107
	v_sin_f32_e32 v144, v107
	v_mul_f32_e32 v107, 0.15915494, v105
	v_rndne_f32_e32 v107, v107
	v_fmac_f32_e32 v105, 0xc0c90fdb, v107
	v_fmac_f32_e32 v105, 0x343bbd2e, v107
	v_mul_f32_e32 v105, 0.15915494, v105
	v_cos_f32_e32 v146, v105
	v_sin_f32_e32 v150, v105
	v_mul_f32_e32 v105, v95, v168
	v_mul_f32_e32 v107, 0.15915494, v105
	v_rndne_f32_e32 v107, v107
	v_fmac_f32_e32 v105, 0xc0c90fdb, v107
	v_fmac_f32_e32 v105, 0x343bbd2e, v107
	v_mul_f32_e32 v105, 0.15915494, v105
	v_mul_f32_e32 v95, v95, v179
	v_cos_f32_e32 v153, v105
	v_sin_f32_e32 v155, v105
	v_mul_f32_e32 v105, 0.15915494, v95
	v_rndne_f32_e32 v105, v105
	v_fmac_f32_e32 v95, 0xc0c90fdb, v105
	v_fmac_f32_e32 v95, 0x343bbd2e, v105
	v_mul_f32_e32 v95, 0.15915494, v95
	v_cos_f32_e32 v149, v95
	v_sin_f32_e32 v157, v95
	v_mul_f32_e32 v95, v93, v168
	v_mul_f32_e32 v105, 0.15915494, v95
	v_rndne_f32_e32 v105, v105
	v_fmac_f32_e32 v95, 0xc0c90fdb, v105
	v_fmac_f32_e32 v95, 0x343bbd2e, v105
	v_mul_f32_e32 v95, 0.15915494, v95
	v_mul_f32_e32 v93, v93, v179
	v_cos_f32_e32 v152, v95
	v_sin_f32_e32 v154, v95
	v_mul_f32_e32 v95, 0.15915494, v93
	v_rndne_f32_e32 v95, v95
	v_fmac_f32_e32 v93, 0xc0c90fdb, v95
	v_fmac_f32_e32 v93, 0x343bbd2e, v95
	v_mul_f32_e32 v93, 0.15915494, v93
	v_cos_f32_e32 v148, v93
	v_sin_f32_e32 v156, v93
	v_mul_f32_e32 v93, v178, v179
	v_mul_f32_e32 v95, 0.15915494, v93
	v_rndne_f32_e32 v95, v95
	v_fmac_f32_e32 v93, 0xc0c90fdb, v95
	v_fmac_f32_e32 v93, 0x343bbd2e, v95
	v_mul_f32_e32 v104, v104, v179
	v_mul_f32_e32 v93, 0.15915494, v93
	s_waitcnt vmcnt(13)
	v_and_b32_e32 v179, 0xffff0000, v197
	v_and_b32_e32 v183, 0xffff0000, v196
	v_sin_f32_e32 v105, v93
	v_cos_f32_e32 v107, v93
	v_mul_f32_e32 v93, v178, v168
	v_lshlrev_b32_e32 v178, 16, v197
	v_lshlrev_b32_e32 v182, 16, v196
	v_mov_b32_e32 v186, v179
	v_mov_b32_e32 v187, v183
	v_mov_b32_e32 v184, v178
	v_mov_b32_e32 v185, v182
	v_pk_mul_f32 v[186:187], v[186:187], v[186:187]
	s_waitcnt vmcnt(12)
	v_and_b32_e32 v181, 0xffff0000, v43
	v_pk_fma_f32 v[230:231], v[184:185], v[184:185], v[186:187]
	v_and_b32_e32 v187, 0xffff0000, v42
	v_lshlrev_b32_e32 v180, 16, v43
	v_lshlrev_b32_e32 v186, 16, v42
	v_mov_b32_e32 v184, v181
	v_mov_b32_e32 v185, v187
	v_mov_b32_e32 v42, v180
	v_mov_b32_e32 v43, v186
	v_pk_mul_f32 v[184:185], v[184:185], v[184:185]
	v_and_b32_e32 v189, 0xffff0000, v41
	v_pk_fma_f32 v[232:233], v[42:43], v[42:43], v[184:185]
	v_and_b32_e32 v185, 0xffff0000, v195
	v_and_b32_e32 v43, 0xffff0000, v194
	v_lshlrev_b32_e32 v184, 16, v195
	v_lshlrev_b32_e32 v42, 16, v194
	v_mov_b32_e32 v194, v185
	v_mov_b32_e32 v195, v43
	v_mov_b32_e32 v190, v184
	v_mov_b32_e32 v191, v42
	v_pk_mul_f32 v[194:195], v[194:195], v[194:195]
	v_lshlrev_b32_e32 v188, 16, v41
	v_pk_fma_f32 v[234:235], v[190:191], v[190:191], v[194:195]
	v_and_b32_e32 v191, 0xffff0000, v40
	v_lshlrev_b32_e32 v190, 16, v40
	v_mov_b32_e32 v194, v189
	v_mov_b32_e32 v195, v191
	v_and_b32_e32 v199, 0xffff0000, v34
	v_mul_f32_e32 v106, 0.15915494, v104
	v_mul_f32_e32 v136, 0.15915494, v134
	v_mov_b32_e32 v40, v188
	v_mov_b32_e32 v41, v190
	v_pk_mul_f32 v[194:195], v[194:195], v[194:195]
	v_and_b32_e32 v197, 0xffff0000, v38
	v_lshlrev_b32_e32 v198, 16, v34
	v_mul_f32_e32 v34, v199, v199
	v_rndne_f32_e32 v106, v106
	v_rndne_f32_e32 v136, v136
	v_pk_fma_f32 v[236:237], v[40:41], v[40:41], v[194:195]
	v_lshlrev_b32_e32 v194, 16, v35
	v_and_b32_e32 v195, 0xffff0000, v35
	v_lshlrev_b32_e32 v196, 16, v38
	v_mul_f32_e32 v38, v197, v197
	v_pk_fma_f32 v[244:245], v[198:199], v[198:199], v[34:35] op_sel_hi:[1,1,0]
	v_and_b32_e32 v35, 0xffff0000, v37
	v_fmac_f32_e32 v104, 0xc0c90fdb, v106
	v_fmac_f32_e32 v134, 0xc0c90fdb, v136
	v_pk_fma_f32 v[242:243], v[196:197], v[196:197], v[38:39] op_sel_hi:[1,1,0]
	v_lshlrev_b32_e32 v34, 16, v37
	v_mul_f32_e32 v38, v35, v35
	v_and_b32_e32 v201, 0xffff0000, v33
	v_fmac_f32_e32 v104, 0x343bbd2e, v106
	v_fmac_f32_e32 v134, 0x343bbd2e, v136
	v_pk_fma_f32 v[246:247], v[34:35], v[34:35], v[38:39] op_sel_hi:[1,1,0]
	v_lshlrev_b32_e32 v200, 16, v33
	v_mul_f32_e32 v38, v201, v201
	v_mul_f32_e32 v104, 0.15915494, v104
	v_mul_f32_e32 v136, 0.15915494, v134
	v_mul_f32_e32 v95, 0.15915494, v93
	v_lshlrev_b32_e32 v40, 16, v39
	v_and_b32_e32 v41, 0xffff0000, v39
	v_pk_fma_f32 v[248:249], v[200:201], v[200:201], v[38:39] op_sel_hi:[1,1,0]
	v_and_b32_e32 v39, 0xffff0000, v36
	v_cos_f32_e32 v106, v104
	v_sin_f32_e32 v104, v104
	v_cos_f32_e32 v134, v136
	v_sin_f32_e32 v136, v136
	v_rndne_f32_e32 v95, v95
	v_lshlrev_b32_e32 v38, 16, v36
	v_mul_f32_e32 v36, v39, v39
	v_fmac_f32_e32 v93, 0xc0c90fdb, v95
	s_waitcnt vmcnt(7)
; __device__ __forceinline__ unsigned pk(float lo, float hi) { f32x2_t v = {lo, hi}; bf16x2_t b = __builtin_convertvector(v, bf16x2_t); return __builtin_bit_cast(unsigned, b); }
; __device__ __forceinline__ float pairsum(float v) { auto rr = __builtin_amdgcn_permlane32_swap(__float_as_uint(v), __float_as_uint(v), false, false); return __uint_as_float(rr[0]) + __uint_as_float(rr[1]); }
;     ...
;             ss = pairsum(ss);
;             const float rstd = rsqrtf(ss * (1.0f / 64.0f) + EPSN) * C2_64;
; #pragma unroll
;             for (int d0 = 0; d0 < 4; ++d0)
; #pragma unroll
;                 for (int j = 0; j < 8; ++j) v[d0][j] *= rstd * U.gain[16 * d0 + 8 * hi + j];
;             const int row = pos >> 6, col = pos & 63;
; #pragma unroll
;             for (int j = 0; j < 8; ++j) {
;                 __builtin_amdgcn_sched_barrier(0);
;                 const float fi = hi ? invf_c(8 + j) : invf_c(j); float c, s;
;                 rope_cs(row, fi, c, s); { const float x1 = v[0][j], x2 = v[1][j]; v[0][j] = x1 * c - x2 * s; v[1][j] = x2 * c + x1 * s; }
;                 rope_cs(col, fi, c, s); { const float x1 = v[2][j], x2 = v[3][j]; v[2][j] = x1 * c - x2 * s; v[3][j] = x2 * c + x1 * s; }
;             }
; #pragma unroll
;             for (int d0 = 0; d0 < 4; ++d0) { u32x4 w; w.x = pk(v[d0][0], v[d0][1]); w.y = pk(v[d0][2], v[d0][3]); w.z = pk(v[d0][4], v[d0][5]); w.w = pk(v[d0][6], v[d0][7]); qf[qb][d0] = __builtin_bit_cast(bf16x8, w); }
	v_mov_b32_e32 v132, v68
	v_mul_f32_e32 v68, v41, v41
	v_pk_fma_f32 v[250:251], v[38:39], v[38:39], v[36:37] op_sel_hi:[1,1,0]
	v_and_b32_e32 v37, 0xffff0000, v32
	v_fmac_f32_e32 v93, 0x343bbd2e, v95
	s_waitcnt vmcnt(3)
	v_pk_fma_f32 v[238:239], v[40:41], v[40:41], v[68:69] op_sel_hi:[1,1,0]
	v_mul_f32_e32 v68, v195, v195
	v_lshlrev_b32_e32 v36, 16, v32
	v_mul_f32_e32 v32, v37, v37
	v_mul_f32_e32 v92, 0.15915494, v92
	v_mul_f32_e32 v95, 0.15915494, v93
	v_pk_fma_f32 v[240:241], v[194:195], v[194:195], v[68:69] op_sel_hi:[1,1,0]
	v_mov_b32_e32 v68, v60
	v_mov_b32_e32 v60, v64
	v_pk_fma_f32 v[32:33], v[36:37], v[36:37], v[32:33] op_sel_hi:[1,1,0]
	v_pk_add_f32 v[246:247], v[250:251], v[246:247]
	v_cos_f32_e32 v94, v92
	v_sin_f32_e32 v92, v92
	v_sin_f32_e32 v93, v95
	v_cos_f32_e32 v95, v95
	v_pk_add_f32 v[242:243], v[242:243], v[246:247]
	s_nop 0
	v_pk_add_f32 v[238:239], v[238:239], v[242:243]
	s_mov_b32 s8, 0x3c800000
	v_pk_add_f32 v[32:33], v[32:33], v[238:239]
	s_mov_b32 s33, 0
	v_pk_add_f32 v[32:33], v[248:249], v[32:33]
	s_nop 0
	v_pk_add_f32 v[32:33], v[244:245], v[32:33]
	s_nop 0
	v_pk_add_f32 v[32:33], v[240:241], v[32:33]
	s_nop 0
	v_pk_add_f32 v[32:33], v[234:235], v[32:33] op_sel:[1,0] op_sel_hi:[0,1]
	v_pk_add_f32 v[32:33], v[234:235], v[32:33]
	s_nop 0
	v_pk_add_f32 v[32:33], v[230:231], v[32:33] op_sel:[1,0] op_sel_hi:[0,1]
	v_pk_add_f32 v[32:33], v[230:231], v[32:33]
	s_nop 0
	v_pk_add_f32 v[32:33], v[236:237], v[32:33] op_sel:[1,0] op_sel_hi:[0,1]
	v_pk_add_f32 v[32:33], v[236:237], v[32:33]
	s_nop 0
	v_pk_add_f32 v[32:33], v[232:233], v[32:33] op_sel:[1,0] op_sel_hi:[0,1]
	v_pk_add_f32 v[32:33], v[232:233], v[32:33]
	s_nop 0
	v_mov_b32_e32 v64, v32
	s_nop 1
	v_permlane32_swap_b32_e32 v32, v64
	v_mov_b32_e32 v33, v192
	v_pk_add_f32 v[32:33], v[32:33], v[64:65]
	s_nop 0
	v_pk_fma_f32 v[32:33], v[32:33], s[8:9], v[170:171] op_sel_hi:[1,0,0]
	s_nop 0
	v_mul_f32_e32 v64, 0x4b800000, v33
	v_cmp_gt_f32_e32 vcc, s71, v33
	s_nop 1
	v_cndmask_b32_e32 v33, v33, v64, vcc
	v_rsq_f32_e32 v33, v33
	s_nop 0
	v_mul_f32_e32 v64, 0x45800000, v33
	v_cndmask_b32_e32 v33, v33, v64, vcc
	v_mul_f32_e32 v64, 0x3e38aa3b, v33
	v_pk_mul_f32 v[8:9], v[8:9], v[64:65] op_sel_hi:[1,0]
	v_pk_mul_f32 v[12:13], v[12:13], v[64:65] op_sel_hi:[1,0]
	v_pk_mul_f32 v[8:9], v[8:9], v[174:175]
	v_pk_mul_f32 v[12:13], v[12:13], v[176:177]
	v_pk_mul_f32 v[14:15], v[14:15], v[64:65] op_sel_hi:[1,0]
	v_pk_mul_f32 v[56:57], v[56:57], v[64:65] op_sel_hi:[1,0]
	v_pk_mul_f32 v[82:83], v[82:83], v[64:65] op_sel_hi:[1,0]
	v_pk_mul_f32 v[10:11], v[64:65], v[10:11] op_sel_hi:[0,1]
	v_pk_mul_f32 v[52:53], v[64:65], v[52:53] op_sel_hi:[0,1]
	v_pk_mul_f32 v[54:55], v[64:65], v[54:55] op_sel_hi:[0,1]
	v_pk_mul_f32 v[4:5], v[64:65], v[4:5] op_sel_hi:[0,1]
	v_pk_mul_f32 v[6:7], v[64:65], v[6:7] op_sel_hi:[0,1]
	v_pk_mul_f32 v[48:49], v[64:65], v[48:49] op_sel_hi:[0,1]
	v_pk_mul_f32 v[50:51], v[64:65], v[50:51] op_sel_hi:[0,1]
	v_pk_mul_f32 v[0:1], v[64:65], v[0:1] op_sel_hi:[0,1]
	v_pk_mul_f32 v[2:3], v[64:65], v[2:3] op_sel_hi:[0,1]
	v_pk_mul_f32 v[44:45], v[64:65], v[44:45] op_sel_hi:[0,1]
	v_pk_mul_f32 v[46:47], v[64:65], v[46:47] op_sel_hi:[0,1]
	v_pk_mul_f32 v[64:65], v[74:75], v[8:9]
	v_pk_mul_f32 v[0:1], v[0:1], v[130:131]
	v_pk_fma_f32 v[64:65], v[76:77], v[12:13], v[64:65] neg_lo:[0,0,1] neg_hi:[0,0,1]
	v_pk_mul_f32 v[12:13], v[74:75], v[12:13]
	v_pk_mul_f32 v[10:11], v[10:11], v[166:167]
	v_pk_mul_f32 v[4:5], v[4:5], v[128:129]
	v_pk_fma_f32 v[8:9], v[76:77], v[8:9], v[12:13]
	v_pk_mul_f32 v[12:13], v[78:79], v[0:1]
	v_pk_mul_f32 v[0:1], v[80:81], v[0:1]
	v_pk_mul_f32 v[14:15], v[14:15], v[172:173]
	v_pk_mul_f32 v[2:3], v[2:3], v[124:125]
	v_pk_fma_f32 v[74:75], v[80:81], v[4:5], v[12:13] neg_lo:[0,0,1] neg_hi:[0,0,1]
	v_pk_fma_f32 v[76:77], v[78:79], v[4:5], v[0:1]
	v_pk_mul_f32 v[4:5], v[86:87], v[10:11]
	v_pk_mul_f32 v[52:53], v[52:53], v[162:163]
	v_pk_mul_f32 v[6:7], v[6:7], v[126:127]
	v_pk_mul_f32 v[0:1], v[84:85], v[10:11]
	v_pk_fma_f32 v[78:79], v[84:85], v[14:15], v[4:5]
	v_pk_mul_f32 v[4:5], v[88:89], v[2:3]
	v_pk_mul_f32 v[56:57], v[56:57], v[164:165]
	v_pk_mul_f32 v[44:45], v[44:45], v[122:123]
	v_pk_fma_f32 v[0:1], v[86:87], v[14:15], v[0:1] neg_lo:[0,0,1] neg_hi:[0,0,1]
	v_pk_fma_f32 v[80:81], v[90:91], v[6:7], v[4:5] neg_lo:[0,0,1] neg_hi:[0,0,1]
	v_pk_mul_f32 v[2:3], v[90:91], v[2:3]
	v_pk_mul_f32 v[4:5], v[98:99], v[52:53]
	v_pk_mul_f32 v[54:55], v[54:55], v[158:159]
	v_pk_mul_f32 v[48:49], v[48:49], v[120:121]
	v_pk_mul_f32 v[46:47], v[46:47], v[116:117]
	v_pk_fma_f32 v[84:85], v[88:89], v[6:7], v[2:3]
	v_pk_mul_f32 v[2:3], v[96:97], v[52:53]
	v_pk_fma_f32 v[52:53], v[96:97], v[56:57], v[4:5]
	v_pk_mul_f32 v[4:5], v[100:101], v[44:45]
	v_cvt_pk_bf16_f32 v117, v0, v1
	v_add_u32_e32 v0, s36, v229
	v_lshlrev_b32_e32 v1, 4, v229
	v_pk_mul_f32 v[82:83], v[82:83], v[160:161]
	v_pk_fma_f32 v[2:3], v[98:99], v[56:57], v[2:3] neg_lo:[0,0,1] neg_hi:[0,0,1]
	v_pk_fma_f32 v[56:57], v[102:103], v[48:49], v[4:5] neg_lo:[0,0,1] neg_hi:[0,0,1]
	v_pk_mul_f32 v[4:5], v[102:103], v[44:45]
	v_pk_mul_f32 v[6:7], v[110:111], v[54:55]
	v_ashrrev_i32_e32 v33, 3, v0
	v_and_b32_e32 v86, 0x70, v1
	v_pk_mul_f32 v[50:51], v[50:51], v[118:119]
	v_pk_fma_f32 v[44:45], v[100:101], v[48:49], v[4:5]
	v_pk_fma_f32 v[48:49], v[108:109], v[82:83], v[6:7]
	v_pk_mul_f32 v[6:7], v[112:113], v[46:47]
	v_lshl_or_b32 v168, v33, 8, v86
	v_pk_mul_f32 v[4:5], v[108:109], v[54:55]
	v_pk_fma_f32 v[54:55], v[114:115], v[50:51], v[6:7] neg_lo:[0,0,1] neg_hi:[0,0,1]
	v_pk_mul_f32 v[6:7], v[114:115], v[46:47]
	v_cvt_pk_bf16_f32 v116, v64, v65
	v_lshl_add_u64 v[64:65], s[4:5], 0, v[168:169]
; __device__ __forceinline__ unsigned pk(float lo, float hi) { f32x2_t v = {lo, hi}; bf16x2_t b = __builtin_convertvector(v, bf16x2_t); return __builtin_bit_cast(unsigned, b); }
; #define BAR_LDS() asm volatile("s_waitcnt lgkmcnt(0)\n\ts_barrier" ::: "memory")
; #define ATT_LOADS(RK, RR, RV, tt) do { RK = *(const u32x4*)((const char*)(U.k + (size_t)(tt) * 64 * KP) + kgo); if (MODE == 2) RR = *(const u32x2*)((const char*)(U.kr + (size_t)(tt) * 64 * 32) + krgo); \
;         RV = *(const u32x4*)((const char*)(U.vt + (size_t)(tt) * VTS) + vgo); } while (0)
;     ...
;             const float rstd = rsqrtf(ss * (1.0f / 64.0f) + EPSN) * C2_64;
; #pragma unroll
;             for (int d0 = 0; d0 < 4; ++d0)
; #pragma unroll
;                 for (int j = 0; j < 8; ++j) v[d0][j] *= rstd * U.gain[16 * d0 + 8 * hi + j];
;             const int row = pos >> 6, col = pos & 63;
; #pragma unroll
;             for (int j = 0; j < 8; ++j) {
;                 __builtin_amdgcn_sched_barrier(0);
;                 const float fi = hi ? invf_c(8 + j) : invf_c(j); float c, s;
;                 rope_cs(row, fi, c, s); { const float x1 = v[0][j], x2 = v[1][j]; v[0][j] = x1 * c - x2 * s; v[1][j] = x2 * c + x1 * s; }
;                 rope_cs(col, fi, c, s); { const float x1 = v[2][j], x2 = v[3][j]; v[2][j] = x1 * c - x2 * s; v[3][j] = x2 * c + x1 * s; }
;             }
; #pragma unroll
;             for (int d0 = 0; d0 < 4; ++d0) { u32x4 w; w.x = pk(v[d0][0], v[d0][1]); w.y = pk(v[d0][2], v[d0][3]); w.z = pk(v[d0][4], v[d0][5]); w.w = pk(v[d0][6], v[d0][7]); qf[qb][d0] = __builtin_bit_cast(bf16x8, w); }
; template <int MODE, bool FAST> __device__ __forceinline__ bool attn_unit(LAS unsigned char* lds, const AttU& U, const int wv) {
;     ...
;     const int krow = tid >> 3, kc = tid & 7;
;     const unsigned kgo = (unsigned)(krow * KP + kc * 8) * 2u, krgo = (unsigned)(krow * 32 + kc * 4) * 2u, vgo = (unsigned)tid * 16u;
;     const unsigned kdst = krow * KSTR + kc * 16, krdst = krow * KSTR + 128 + kc * 8, vdst = 64 * KSTR + krow * VSTR + kc * 16;
;     u32x4 rk, rv, rk2, rv2; u32x2 rr = {0u, 0u}, rr2 = {0u, 0u};
;     ...
;     const int NT = U.kt1 - U.kt0;
;     ATT_LOAD(U.kt0); ATT_STORE(0);
;     if (NT > 1) { ATT_LOAD(U.kt0 + 1); ATT_STORE(1); }
;     if (NT > 2) ATT_LOAD(U.kt0 + 2);
;     if constexpr (FAST) { if (NT > 3) ATT_LOADS(rk2, rr2, rv2, U.kt0 + 3); }
;     BAR_LDS();
	v_pk_fma_f32 v[46:47], v[112:113], v[50:51], v[6:7]
	v_cvt_pk_bf16_f32 v120, v8, v9
	v_lshlrev_b32_e32 v50, 4, v0
	v_mov_b32_e32 v51, v169
	v_add_co_u32_e32 v8, vcc, s72, v64
	v_pk_fma_f32 v[4:5], v[110:111], v[82:83], v[4:5] neg_lo:[0,0,1] neg_hi:[0,0,1]
	v_lshl_add_u64 v[82:83], s[6:7], 0, v[50:51]
	v_addc_co_u32_e32 v9, vcc, 0, v65, vcc
	v_add_co_u32_e32 v12, vcc, s72, v82
	v_cvt_pk_bf16_f32 v118, v2, v3
	s_nop 0
	v_addc_co_u32_e32 v13, vcc, 0, v83, vcc
	v_cvt_pk_bf16_f32 v119, v4, v5
	global_load_dwordx4 v[0:3], v168, s[4:5]
	global_load_dwordx4 v[4:7], v50, s[6:7]
	s_nop 0
	global_load_dwordx4 v[8:11], v[8:9], off
	s_nop 0
	global_load_dwordx4 v[12:15], v[12:13], off
	v_cvt_pk_bf16_f32 v123, v48, v49
	v_mul_f32_e32 v48, 0x4b800000, v32
	v_cmp_gt_f32_e32 vcc, s71, v32
	v_cvt_pk_bf16_f32 v130, v44, v45
	v_cvt_pk_bf16_f32 v122, v52, v53
	v_cndmask_b32_e32 v32, v32, v48, vcc
	v_rsq_f32_e32 v32, v32
	v_cvt_pk_bf16_f32 v126, v56, v57
	v_cvt_pk_bf16_f32 v127, v54, v55
	v_cvt_pk_bf16_f32 v131, v46, v47
	v_mul_f32_e32 v44, 0x45800000, v32
	v_cndmask_b32_e32 v32, v32, v44, vcc
	v_mul_f32_e32 v32, 0x3e38aa3b, v32
	v_pk_mul_f32 v[30:31], v[32:33], v[30:31] op_sel_hi:[0,1]
	v_pk_mul_f32 v[26:27], v[32:33], v[26:27] op_sel_hi:[0,1]
	v_pk_mul_f32 v[30:31], v[30:31], v[188:189]
	v_pk_mul_f32 v[18:19], v[18:19], v[32:33] op_sel_hi:[1,0]
	v_pk_mul_f32 v[22:23], v[32:33], v[22:23] op_sel_hi:[0,1]
	v_pk_mul_f32 v[26:27], v[26:27], v[184:185]
	v_pk_mul_f32 v[18:19], v[18:19], v[34:35]
	v_pk_mul_f32 v[22:23], v[22:23], v[200:201]
	v_pk_mul_f32 v[34:35], v[142:143], v[30:31]
	v_pk_mul_f32 v[30:31], v[144:145], v[30:31]
	v_pk_mul_f32 v[48:49], v[68:69], v[32:33] op_sel_hi:[1,0]
	v_pk_fma_f32 v[34:35], v[144:145], v[26:27], v[34:35]
	v_pk_fma_f32 v[26:27], v[142:143], v[26:27], v[30:31] neg_lo:[0,0,1] neg_hi:[0,0,1]
	v_pk_mul_f32 v[30:31], v[146:147], v[22:23]
	v_pk_mul_f32 v[22:23], v[150:151], v[22:23]
	s_waitcnt vmcnt(5)
	v_pk_mul_f32 v[44:45], v[32:33], v[132:133] op_sel_hi:[0,1]
	s_waitcnt vmcnt(4)
	v_pk_mul_f32 v[46:47], v[32:33], v[72:73] op_sel_hi:[0,1]
	v_pk_mul_f32 v[40:41], v[48:49], v[40:41]
	v_pk_mul_f32 v[48:49], v[32:33], v[60:61] op_sel_hi:[0,1]
	v_pk_mul_f32 v[52:53], v[32:33], v[66:67] op_sel_hi:[0,1]
	v_pk_mul_f32 v[54:55], v[32:33], v[70:71] op_sel_hi:[0,1]
	v_pk_mul_f32 v[56:57], v[58:59], v[32:33] op_sel_hi:[1,0]
	v_pk_mul_f32 v[58:59], v[32:33], v[62:63] op_sel_hi:[0,1]
	v_pk_fma_f32 v[30:31], v[150:151], v[18:19], v[30:31]
	v_pk_fma_f32 v[18:19], v[146:147], v[18:19], v[22:23] neg_lo:[0,0,1] neg_hi:[0,0,1]
	v_pk_mul_f32 v[22:23], v[32:33], v[24:25] op_sel_hi:[0,1]
	v_pk_mul_f32 v[24:25], v[32:33], v[28:29] op_sel_hi:[0,1]
	v_pk_mul_f32 v[16:17], v[16:17], v[32:33] op_sel_hi:[1,0]
	v_pk_mul_f32 v[20:21], v[20:21], v[32:33] op_sel_hi:[1,0]
	v_mul_lo_u32 v33, v33, s60
	v_add3_u32 v173, v33, v86, 0
	s_waitcnt vmcnt(3)
	ds_write_b128 v173, v[0:3]
	s_waitcnt vmcnt(2)
	ds_write_b128 v173, v[4:7] offset:9216
	s_waitcnt vmcnt(1)
	ds_write_b128 v173, v[8:11] offset:18432
	s_waitcnt vmcnt(0)
	ds_write_b128 v173, v[12:15] offset:27648
	v_add_co_u32_e32 v0, vcc, s73, v64
	v_pk_mul_f32 v[54:55], v[54:55], v[186:187]
	s_nop 0
	v_addc_co_u32_e32 v1, vcc, 0, v65, vcc
	v_pk_mul_f32 v[52:53], v[52:53], v[182:183]
	v_pk_mul_f32 v[58:59], v[58:59], v[198:199]
	v_pk_mul_f32 v[60:61], v[134:135], v[54:55]
	v_pk_mul_f32 v[54:55], v[136:137], v[54:55]
	v_add_co_u32_e32 v2, vcc, s73, v82
	v_pk_mul_f32 v[56:57], v[56:57], v[196:197]
	v_pk_fma_f32 v[60:61], v[136:137], v[52:53], v[60:61]
	v_pk_fma_f32 v[52:53], v[134:135], v[52:53], v[54:55] neg_lo:[0,0,1] neg_hi:[0,0,1]
	v_pk_mul_f32 v[54:55], v[138:139], v[58:59]
	v_pk_mul_f32 v[58:59], v[140:141], v[58:59]
	v_addc_co_u32_e32 v3, vcc, 0, v83, vcc
	v_pk_fma_f32 v[54:55], v[140:141], v[56:57], v[54:55]
	v_pk_fma_f32 v[56:57], v[138:139], v[56:57], v[58:59] neg_lo:[0,0,1] neg_hi:[0,0,1]
	global_load_dwordx4 v[132:135], v[0:1], off
	global_load_dwordx4 v[136:139], v[2:3], off
	v_add_co_u32_e32 v0, vcc, s74, v64
	v_bfe_u32 v32, v229, 5, 1
	s_nop 0
	v_addc_co_u32_e32 v1, vcc, 0, v65, vcc
	v_add_co_u32_e32 v2, vcc, s74, v82
	v_lshlrev_b32_e32 v172, 4, v32
	s_nop 0
	v_addc_co_u32_e32 v3, vcc, 0, v83, vcc
	global_load_dwordx4 v[140:143], v[0:1], off
	global_load_dwordx4 v[144:147], v[2:3], off
	v_mul_u32_u24_e32 v0, 0x90, v227
	s_waitcnt lgkmcnt(0)
	s_barrier
; #define LAS __attribute__((address_space(3)))
; template <int MODE, bool FAST> __device__ __forceinline__ bool attn_unit(LAS unsigned char* lds, const AttU& U, const int wv) {
;     ...
;     f32x16 o[2][2];
; #pragma unroll
;     for (int a = 0; a < 2; ++a)
; #pragma unroll
;         for (int b = 0; b < 2; ++b)
; #pragma unroll
;             for (int r = 0; r < 16; ++r) o[a][b][r] = 0.f;
;     ...
;     pb[1][0] = (bf16x8){0, 0, 0, 0, 0, 0, 0, 0}; pb[1][1] = pb[1][0];
;     ATT_QK(0, 0, 0);
;     bf16x8 kpre[NPRE > 0 ? NPRE : 1];
; #pragma unroll
;     for (int i_ = 0; i_ < NPRE; ++i_) kpre[i_] = *(LAS const bf16x8*)(lds + koff + i_ * 32);
;     ...
;     if constexpr (FAST) {
;         for (int t2 = U.kt0; t2 < U.kt1; t2 += 2) { ATT_TILE(t2, 4, rk, rr, rv); ATT_TILE(t2 + 1, 4, rk2, rr2, rv2); }
	v_add3_u32 v184, v172, v0, 0
	v_cvt_pk_bf16_f32 v125, v80, v81
	ds_read_b128 v[80:83], v184
	ds_read_b128 v[108:111], v184 offset:32
	v_cvt_pk_bf16_f32 v121, v78, v79
	v_cvt_pk_bf16_f32 v124, v74, v75
	v_cvt_pk_bf16_f32 v128, v76, v77
	s_waitcnt lgkmcnt(1)
	v_mfma_f32_32x32x16_bf16 v[64:79], v[80:83], v[116:119], 0
	v_mul_f32_e64 v48, v48, v194
	v_mul_f32_e64 v49, v49, v195
	v_mul_f32_e64 v24, v24, v190
	v_mul_f32_e64 v25, v25, v191
	v_mul_f32_e64 v2, v104, v48
	v_mul_f32_e64 v3, v105, v49
	v_pk_mul_f32 v[4:5], v[106:107], v[48:49]
	v_pk_fma_f32 v[2:3], v[106:107], v[40:41], v[2:3] neg_lo:[0,0,1] neg_hi:[0,0,1]
	v_pk_fma_f32 v[4:5], v[104:105], v[40:41], v[4:5]
	ds_read_b128 v[104:107], v184 offset:64
	s_waitcnt lgkmcnt(1)
	v_mfma_f32_32x32x16_bf16 v[64:79], v[108:111], v[120:123], v[64:79]
	v_mul_f32_e64 v22, v22, v42
	v_mul_f32_e64 v23, v23, v43
	v_mul_f32_e64 v16, v16, v38
	v_mul_f32_e64 v17, v17, v39
	v_mul_f32_e64 v28, v152, v24
	v_mul_f32_e64 v29, v153, v25
	v_pk_mul_f32 v[24:25], v[154:155], v[24:25]
	v_pk_mul_f32 v[20:21], v[20:21], v[36:37]
	v_pk_fma_f32 v[28:29], v[154:155], v[22:23], v[28:29]
	v_pk_fma_f32 v[22:23], v[152:153], v[22:23], v[24:25] neg_lo:[0,0,1] neg_hi:[0,0,1]
	v_pk_mul_f32 v[24:25], v[156:157], v[16:17]
	v_cvt_pk_bf16_f32 v151, v2, v3
	v_pk_fma_f32 v[24:25], v[148:149], v[20:21], v[24:25]
	v_pk_mul_f32 v[20:21], v[156:157], v[20:21]
	v_cvt_pk_bf16_f32 v129, v84, v85
	v_pk_fma_f32 v[0:1], v[148:149], v[16:17], v[20:21] neg_lo:[0,0,1] neg_hi:[0,0,1]
	v_pk_mul_f32 v[46:47], v[46:47], v[180:181]
	v_cvt_pk_bf16_f32 v148, v0, v1
	ds_read_b128 v[0:3], v184 offset:96
	s_waitcnt lgkmcnt(1)
	v_mfma_f32_32x32x16_bf16 v[64:79], v[104:107], v[124:127], v[64:79]
	v_mul_f32_e64 v44, v44, v178
	v_mul_f32_e64 v45, v45, v179
	v_mul_f32_e64 v6, v92, v46
	v_mul_f32_e64 v7, v93, v47
	v_mul_f32_e64 v8, v94, v46
	v_mul_f32_e64 v9, v95, v47
	v_pk_fma_f32 v[6:7], v[94:95], v[44:45], v[6:7] neg_lo:[0,0,1] neg_hi:[0,0,1]
	v_pk_fma_f32 v[8:9], v[92:93], v[44:45], v[8:9]
	v_mov_b32_e32 v48, 0
	v_cvt_pk_bf16_f32 v149, v18, v19
	s_waitcnt lgkmcnt(0)
	v_mfma_f32_32x32x16_bf16 v[64:79], v[0:3], v[128:131], v[64:79]
	v_cvt_pk_bf16_f32 v150, v56, v57
	v_cvt_pk_bf16_f32 v152, v24, v25
	v_cvt_pk_bf16_f32 v153, v30, v31
	v_cvt_pk_bf16_f32 v154, v54, v55
	v_cvt_pk_bf16_f32 v155, v4, v5
	v_cvt_pk_bf16_f32 v156, v22, v23
	v_cvt_pk_bf16_f32 v157, v26, v27
	v_cvt_pk_bf16_f32 v158, v52, v53
	v_cvt_pk_bf16_f32 v159, v6, v7
	v_cvt_pk_bf16_f32 v160, v28, v29
	v_cvt_pk_bf16_f32 v161, v34, v35
	v_cvt_pk_bf16_f32 v162, v60, v61
	v_cvt_pk_bf16_f32 v163, v8, v9
	v_mov_b32_e32 v174, v168
	v_mov_b32_e32 v176, v50
	s_add_u32 s98, s46, s14
	s_addc_u32 s99, s47, s15
	s_add_u32 s98, s98, 0x12310000
	s_addc_u32 s99, s99, 0
	s_add_u32 s100, s46, s42
	s_addc_u32 s101, s47, s43
	s_add_u32 s100, s100, 0x12f10000
	s_addc_u32 s101, s101, 0
	s_mov_b64 s[42:43], 0
	v_mov_b32_e32 v96, 0
	v_mov_b32_e32 v97, 0
	v_mov_b32_e32 v98, 0
	v_mov_b32_e32 v99, 0
	v_mov_b32_e32 v100, 0
	v_mov_b32_e32 v101, 0
	v_mov_b32_e32 v102, 0
	v_mov_b32_e32 v103, 0
	v_mov_b32_e32 v49, v48
	v_mov_b32_e32 v50, v48
	v_mov_b32_e32 v51, v48
	v_mov_b32_e32 v52, v48
	v_mov_b32_e32 v53, v48
	v_mov_b32_e32 v54, v48
	v_mov_b32_e32 v55, v48
	v_mov_b32_e32 v56, v48
	v_mov_b32_e32 v57, v48
	v_mov_b32_e32 v58, v48
	v_mov_b32_e32 v59, v48
	v_mov_b32_e32 v60, v48
	v_mov_b32_e32 v61, v48
	v_mov_b32_e32 v62, v48
	v_mov_b32_e32 v63, v48
	v_mov_b32_e32 v32, v48
	v_mov_b32_e32 v33, v48
	v_mov_b32_e32 v34, v48
	v_mov_b32_e32 v35, v48
	v_mov_b32_e32 v36, v48
	v_mov_b32_e32 v37, v48
	v_mov_b32_e32 v38, v48
	v_mov_b32_e32 v39, v48
	v_mov_b32_e32 v40, v48
	v_mov_b32_e32 v41, v48
	v_mov_b32_e32 v42, v48
	v_mov_b32_e32 v43, v48
	v_mov_b32_e32 v44, v48
	v_mov_b32_e32 v45, v48
	v_mov_b32_e32 v46, v48
	v_mov_b32_e32 v47, v48
	v_mov_b32_e32 v16, v48
	v_mov_b32_e32 v17, v48
	v_mov_b32_e32 v18, v48
	v_mov_b32_e32 v19, v48
	v_mov_b32_e32 v20, v48
	v_mov_b32_e32 v21, v48
	v_mov_b32_e32 v22, v48
	v_mov_b32_e32 v23, v48
	v_mov_b32_e32 v24, v48
	v_mov_b32_e32 v25, v48
	v_mov_b32_e32 v26, v48
	v_mov_b32_e32 v27, v48
	v_mov_b32_e32 v28, v48
	v_mov_b32_e32 v29, v48
	v_mov_b32_e32 v30, v48
	v_mov_b32_e32 v31, v48
	v_mov_b32_e32 v0, v48
	v_mov_b32_e32 v1, v48
	v_mov_b32_e32 v2, v48
	v_mov_b32_e32 v3, v48
	v_mov_b32_e32 v4, v48
	v_mov_b32_e32 v5, v48
	v_mov_b32_e32 v6, v48
	v_mov_b32_e32 v7, v48
	v_mov_b32_e32 v8, v48
	v_mov_b32_e32 v9, v48
	v_mov_b32_e32 v10, v48
	v_mov_b32_e32 v11, v48
	v_mov_b32_e32 v12, v48
	v_mov_b32_e32 v13, v48
	v_mov_b32_e32 v14, v48
	v_mov_b32_e32 v15, v48
	v_mov_b32_e32 v178, v48
	v_mov_b32_e32 v179, v48
	.p2align 6

;     ...
;     for (int qb = 0; qb < 2; ++qb) {
;         __builtin_amdgcn_sched_barrier(0);
;         const bf16_t* src = U.q + (size_t)(32 * qb + r32) * QP + 8 * hi;
;         u32x4 raw[ND];
; #pragma unroll
;         for (int d0 = 0; d0 < ND; ++d0) raw[d0] = *(const u32x4*)(src + 16 * d0);
;         int pos = U.tq0 + 32 * qb + r32; asm volatile("" : "+v"(pos));
;         if constexpr (MODE == 1) {
; #pragma unroll
;             for (int d0 = 0; d0 < ND; ++d0) qf[qb][d0] = __builtin_bit_cast(bf16x8, raw[d0]);
;         } else if constexpr (MODE == 0) {
;             float v[4][8]; float ss = 0.f;
; #pragma unroll
;             for (int d0 = 0; d0 < 4; ++d0)
; #pragma unroll
;                 for (int j = 0; j < 4; ++j) { const unsigned w = raw[d0][j]; v[d0][2 * j] = bflo(w); v[d0][2 * j + 1] = bfhi(w); ss += v[d0][2 * j] * v[d0][2 * j] + v[d0][2 * j + 1] * v[d0][2 * j + 1]; }
;             ss = pairsum(ss);
;             const float rstd = rsqrtf(ss * (1.0f / 64.0f) + EPSN) * C2_64;
; #pragma unroll
;             for (int d0 = 0; d0 < 4; ++d0)
; #pragma unroll
;                 for (int j = 0; j < 8; ++j) v[d0][j] *= rstd * U.gain[16 * d0 + 8 * hi + j];
;             const int row = pos >> 6, col = pos & 63;
; #pragma unroll
;             for (int j = 0; j < 8; ++j) {
;                 __builtin_amdgcn_sched_barrier(0);
;                 const float fi = hi ? invf_c(8 + j) : invf_c(j); float c, s;
;                 rope_cs(row, fi, c, s); { const float x1 = v[0][j], x2 = v[1][j]; v[0][j] = x1 * c - x2 * s; v[1][j] = x2 * c + x1 * s; }
;                 rope_cs(col, fi, c, s); { const float x1 = v[2][j], x2 = v[3][j]; v[2][j] = x1 * c - x2 * s; v[3][j] = x2 * c + x1 * s; }
;             }
; #pragma unroll
;             for (int d0 = 0; d0 < 4; ++d0) { u32x4 w; w.x = pk(v[d0][0], v[d0][1]); w.y = pk(v[d0][2], v[d0][3]); w.z = pk(v[d0][4], v[d0][5]); w.w = pk(v[d0][6], v[d0][7]); qf[qb][d0] = __builtin_bit_cast(bf16x8, w); }
;         } else {
; #pragma unroll
;             for (int d0 = 0; d0 < 4; ++d0) qf[qb][d0] = __builtin_bit_cast(bf16x8, raw[d0]);
;             float a[8], b[8];
; #pragma unroll
;             for (int j = 0; j < 4; ++j) { a[2 * j] = bflo(raw[ND - 2][j]); a[2 * j + 1] = bfhi(raw[ND - 2][j]); b[2 * j] = bflo(raw[ND - 1][j]); b[2 * j + 1] = bfhi(raw[ND - 1][j]); }
; #pragma unroll
.LBB0_922:
	s_lshr_b64 s[6:7], s[20:21], 4
	s_lshl_b64 s[8:9], s[6:7], 25
	s_add_u32 s40, s18, s8
	s_addc_u32 s41, s19, s9
	s_add_i32 s9, s59, s50
	s_and_b32 s44, s58, 15
	s_lshr_b32 s8, s9, 4
	s_and_b32 s24, s9, 15
	s_mov_b32 s9, s31
	s_lshl_b32 s30, s44, 13
	s_lshl_b64 s[6:7], s[6:7], 20
	s_lshl_b64 s[10:11], s[8:9], 14
	s_add_u32 s22, s10, s63
	s_addc_u32 s23, s11, s66
	s_mul_i32 s10, s23, 0xc00
	s_mul_hi_u32 s11, s22, 0xc00
	s_add_i32 s11, s11, s10
	s_mul_i32 s10, s22, 0xc00
	s_add_u32 s10, s26, s10
	s_addc_u32 s11, s27, s11
	s_mul_i32 s12, s24, 0xc0
	s_add_u32 s42, s10, s12
	s_addc_u32 s43, s11, 0
	s_lshl_b64 s[12:13], s[8:9], 25
	s_add_u32 s10, s33, s12
	s_addc_u32 s11, s37, s13
	s_lshl_b32 s60, s24, 6
	s_lshl_b32 s35, s24, 7
	s_add_u32 s10, s10, s35
	s_addc_u32 s11, s11, 0
	s_lshl_b64 s[8:9], s[8:9], 20
	s_add_u32 s8, s25, s8
	s_addc_u32 s9, s52, s9
	s_add_u32 s12, s46, s12
	s_addc_u32 s13, s47, s13
	s_lshl_b32 s24, s24, 13
	s_add_u32 s12, s12, s24
	v_mbcnt_lo_u32_b32 v8, -1, 0
	v_mbcnt_hi_u32_b32 v8, -1, v8
	s_addc_u32 s13, s13, 0
	v_and_b32_e32 v237, 63, v8
	v_and_b32_e32 v187, 31, v8
	v_cmp_gt_u32_e32 vcc, 32, v237
	v_mul_u32_u24_e32 v0, 0x600, v187
	v_lshlrev_b32_e32 v96, 1, v0
	v_lshrrev_b32_e32 v2, 1, v8
	v_lshl_add_u64 v[0:1], s[42:43], 0, v[96:97]
	v_and_b32_e32 v96, 16, v2
	v_lshl_add_u64 v[10:11], v[0:1], 0, v[96:97]
	global_load_dwordx4 v[0:3], v[10:11], off offset:128
	global_load_dwordx4 v[4:7], v[10:11], off offset:160
	global_load_dwordx4 v[98:101], v[10:11], off
	global_load_dwordx4 v[102:105], v[10:11], off offset:32
	global_load_dwordx4 v[106:109], v[10:11], off offset:64
	global_load_dwordx4 v[110:113], v[10:11], off offset:96
	v_or_b32_e32 v9, s63, v187
	s_waitcnt vmcnt(5)
	v_and_b32_e32 v18, 0xffff0000, v0
	v_cvt_f32_i32_e32 v9, v9
	s_waitcnt vmcnt(4)
	v_and_b32_e32 v19, 0xffff0000, v4
	v_and_b32_e32 v20, 0xffff0000, v1
	v_and_b32_e32 v21, 0xffff0000, v5
	v_and_b32_e32 v22, 0xffff0000, v2
	v_and_b32_e32 v23, 0xffff0000, v6
	v_and_b32_e32 v24, 0xffff0000, v3
	v_and_b32_e32 v25, 0xffff0000, v7
	v_mov_b32_e32 v10, 0x3c23d70a
	v_cndmask_b32_e64 v27, v10, 1.0, vcc
	v_mul_f32_e32 v10, v27, v9
	v_mul_f32_e32 v11, 0.15915494, v10
	v_rndne_f32_e32 v11, v11
	v_fmac_f32_e32 v10, 0xc0c90fdb, v11
	v_fmac_f32_e32 v10, 0x343bbd2e, v11
	v_mul_f32_e32 v11, 0.15915494, v10
	v_sin_f32_e32 v10, v11
	v_cos_f32_e32 v11, v11
	v_lshlrev_b32_e32 v13, 16, v0
	v_lshlrev_b32_e32 v12, 16, v4
	v_mov_b32_e32 v17, v10
	v_mov_b32_e32 v16, v11
	v_pk_mul_f32 v[14:15], v[10:11], v[12:13]
	v_pk_mul_f32 v[10:11], v[16:17], v[12:13]
	v_mov_b32_e32 v0, 0x3bb8449c
	v_mov_b32_e32 v4, 0x3f0ff59a
	v_cndmask_b32_e32 v29, v0, v4, vcc
	v_mul_f32_e32 v0, v29, v9
	v_mul_f32_e32 v4, 0.15915494, v0
	v_rndne_f32_e32 v4, v4
	v_fmac_f32_e32 v0, 0xc0c90fdb, v4
	v_fmac_f32_e32 v0, 0x343bbd2e, v4
	v_mul_f32_e32 v0, 0.15915494, v0
	v_cos_f32_e32 v4, v0
	v_sin_f32_e32 v0, v0
	v_mov_b32_e32 v12, v15
	v_mov_b32_e32 v16, v11
	v_mul_f32_e32 v13, v4, v18
	v_mul_f32_e32 v15, v0, v19
	v_pk_add_f32 v[12:13], v[12:13], v[14:15] neg_lo:[0,1] neg_hi:[0,1]
	v_mul_f32_e32 v15, v4, v19
	v_mul_f32_e32 v17, v0, v18
	v_mov_b32_e32 v14, v10
	v_pk_add_f32 v[10:11], v[14:15], v[16:17]
	v_mov_b32_e32 v0, 0x3b4f3e37
	v_mov_b32_e32 v4, 0x3ea1e89b
	v_cndmask_b32_e32 v47, v0, v4, vcc
	v_mul_f32_e32 v0, v47, v9
	v_mul_f32_e32 v4, 0.15915494, v0
	v_rndne_f32_e32 v4, v4
	v_fmac_f32_e32 v0, 0xc0c90fdb, v4
	v_fmac_f32_e32 v0, 0x343bbd2e, v4
	v_mul_f32_e32 v0, 0.15915494, v0
	v_sin_f32_e32 v14, v0
	v_cos_f32_e32 v15, v0
	v_lshlrev_b32_e32 v1, 16, v1
	v_lshlrev_b32_e32 v0, 16, v5
	v_mov_b32_e32 v17, v14
	v_mov_b32_e32 v16, v15
	v_pk_mul_f32 v[4:5], v[14:15], v[0:1]
	v_pk_mul_f32 v[0:1], v[16:17], v[0:1]
	v_mov_b32_e32 v14, 0x3ae91528
	v_mov_b32_e32 v15, 0x3e361887
	v_cndmask_b32_e32 v53, v14, v15, vcc
	v_mul_f32_e32 v14, v53, v9
	v_mul_f32_e32 v15, 0.15915494, v14
	v_rndne_f32_e32 v15, v15
	v_fmac_f32_e32 v14, 0xc0c90fdb, v15
	v_fmac_f32_e32 v14, 0x343bbd2e, v15
	v_mul_f32_e32 v14, 0.15915494, v14
	v_cos_f32_e32 v16, v14
	v_sin_f32_e32 v17, v14
	v_mov_b32_e32 v14, v5
	v_mul_f32_e32 v15, v16, v20
	v_mul_f32_e32 v5, v17, v21
	v_pk_add_f32 v[4:5], v[14:15], v[4:5] neg_lo:[0,1] neg_hi:[0,1]
	v_mul_f32_e32 v15, v16, v21
	v_mul_f32_e32 v17, v17, v20
	v_mov_b32_e32 v14, v0
	v_mov_b32_e32 v16, v1
	v_pk_add_f32 v[0:1], v[14:15], v[16:17]
	v_mov_b32_e32 v14, 0x3a83126f
	v_mov_b32_e32 v15, 0x3dcccccd
	v_cndmask_b32_e32 v56, v14, v15, vcc
	v_mul_f32_e32 v14, v56, v9
	v_mul_f32_e32 v15, 0.15915494, v14
	v_rndne_f32_e32 v15, v15
	v_fmac_f32_e32 v14, 0xc0c90fdb, v15
	v_fmac_f32_e32 v14, 0x343bbd2e, v15
	v_mul_f32_e32 v15, 0.15915494, v14
	v_sin_f32_e32 v14, v15
	v_cos_f32_e32 v15, v15
	v_lshlrev_b32_e32 v17, 16, v2
	v_lshlrev_b32_e32 v16, 16, v6
	v_mov_b32_e32 v21, v14
	v_mov_b32_e32 v20, v15
	v_pk_mul_f32 v[18:19], v[14:15], v[16:17]
	v_pk_mul_f32 v[14:15], v[20:21], v[16:17]
	v_mov_b32_e32 v2, 0x3d6655c3
	v_cndmask_b32_e32 v57, v193, v2, vcc
	v_mul_f32_e32 v2, v57, v9
	v_mul_f32_e32 v6, 0.15915494, v2
	v_rndne_f32_e32 v6, v6
	v_fmac_f32_e32 v2, 0xc0c90fdb, v6
	v_fmac_f32_e32 v2, 0x343bbd2e, v6
	v_mul_f32_e32 v2, 0.15915494, v2
	v_cos_f32_e32 v6, v2
	v_sin_f32_e32 v2, v2
	v_mov_b32_e32 v16, v19
	v_mov_b32_e32 v20, v15
	v_mul_f32_e32 v17, v6, v22
	v_mul_f32_e32 v19, v2, v23
	v_pk_add_f32 v[16:17], v[16:17], v[18:19] neg_lo:[0,1] neg_hi:[0,1]
	v_mul_f32_e32 v19, v6, v23
	v_mul_f32_e32 v21, v2, v22
	v_mov_b32_e32 v18, v14
	v_pk_add_f32 v[14:15], v[18:19], v[20:21]
	v_mov_b32_e32 v2, 0x39a5cb5f
	v_mov_b32_e32 v6, 0x3d0186e2
	v_cndmask_b32_e32 v22, v2, v6, vcc
	v_mul_f32_e32 v2, v22, v9
	v_mul_f32_e32 v6, 0.15915494, v2
; __device__ __forceinline__ unsigned pk(float lo, float hi) { f32x2_t v = {lo, hi}; bf16x2_t b = __builtin_convertvector(v, bf16x2_t); return __builtin_bit_cast(unsigned, b); }
; #define BAR_LDS() asm volatile("s_waitcnt lgkmcnt(0)\n\ts_barrier" ::: "memory")
; #define ATT_LOADS(RK, RR, RV, tt) do { RK = *(const u32x4*)((const char*)(U.k + (size_t)(tt) * 64 * KP) + kgo); if (MODE == 2) RR = *(const u32x2*)((const char*)(U.kr + (size_t)(tt) * 64 * 32) + krgo); \
;         RV = *(const u32x4*)((const char*)(U.vt + (size_t)(tt) * VTS) + vgo); } while (0)
; #define ATT_LOAD(tt) ATT_LOADS(rk, rr, rv, tt)
; #define ATT_STORE(ss) ATT_STORES(rk, rr, rv, ss)
;     ...
;             for (int j = 0; j < 8; ++j) { __builtin_amdgcn_sched_barrier(0); const float fi = hi ? invf_c(8 + j) : invf_c(j); float c, s; rope_cs(pos, fi, c, s);
;                 const float x1 = a[j], x2 = b[j]; a[j] = x1 * c - x2 * s; b[j] = x2 * c + x1 * s; }
;             u32x4 wa, wb; wa.x = pk(a[0], a[1]); wa.y = pk(a[2], a[3]); wa.z = pk(a[4], a[5]); wa.w = pk(a[6], a[7]); wb.x = pk(b[0], b[1]); wb.y = pk(b[2], b[3]); wb.z = pk(b[4], b[5]); wb.w = pk(b[6], b[7]);
;             qf[qb][ND - 2] = __builtin_bit_cast(bf16x8, wa); qf[qb][ND - 1] = __builtin_bit_cast(bf16x8, wb);
; template <int MODE, bool FAST> __device__ __forceinline__ bool attn_unit(LAS unsigned char* lds, const AttU& U, const int wv) {
;     ...
;     const int krow = tid >> 3, kc = tid & 7;
;     const unsigned kgo = (unsigned)(krow * KP + kc * 8) * 2u, krgo = (unsigned)(krow * 32 + kc * 4) * 2u, vgo = (unsigned)tid * 16u;
;     const unsigned kdst = krow * KSTR + kc * 16, krdst = krow * KSTR + 128 + kc * 8, vdst = 64 * KSTR + krow * VSTR + kc * 16;
;     u32x4 rk, rv, rk2, rv2; u32x2 rr = {0u, 0u}, rr2 = {0u, 0u};
;     ...
;     const int NT = U.kt1 - U.kt0;
;     ATT_LOAD(U.kt0); ATT_STORE(0);
;     if (NT > 1) { ATT_LOAD(U.kt0 + 1); ATT_STORE(1); }
;     if (NT > 2) ATT_LOAD(U.kt0 + 2);
;     if constexpr (FAST) { if (NT > 3) ATT_LOADS(rk2, rr2, rv2, U.kt0 + 3); }
;     BAR_LDS();
	v_rndne_f32_e32 v6, v6
	v_fmac_f32_e32 v2, 0xc0c90fdb, v6
	v_fmac_f32_e32 v2, 0x343bbd2e, v6
	v_mul_f32_e32 v2, 0.15915494, v2
	v_sin_f32_e32 v18, v2
	v_cos_f32_e32 v19, v2
	v_lshlrev_b32_e32 v3, 16, v3
	v_lshlrev_b32_e32 v2, 16, v7
	v_mov_b32_e32 v21, v18
	v_mov_b32_e32 v20, v19
	v_pk_mul_f32 v[6:7], v[18:19], v[2:3]
	v_pk_mul_f32 v[2:3], v[20:21], v[2:3]
	v_cndmask_b32_e32 v86, v234, v235, vcc
	v_mul_f32_e32 v9, v86, v9
	v_mul_f32_e32 v18, 0.15915494, v9
	v_rndne_f32_e32 v18, v18
	v_fmac_f32_e32 v9, 0xc0c90fdb, v18
	v_fmac_f32_e32 v9, 0x343bbd2e, v18
	v_mul_f32_e32 v9, 0.15915494, v9
	v_cos_f32_e32 v20, v9
	v_sin_f32_e32 v9, v9
	v_mov_b32_e32 v18, v7
	v_cvt_pk_bf16_f32 v114, v12, v13
	v_mul_f32_e32 v19, v20, v24
	v_mul_f32_e32 v7, v9, v25
	v_pk_add_f32 v[6:7], v[18:19], v[6:7] neg_lo:[0,1] neg_hi:[0,1]
	v_mul_f32_e32 v19, v20, v25
	v_mul_f32_e32 v21, v9, v24
	v_mov_b32_e32 v18, v2
	v_mov_b32_e32 v20, v3
	v_pk_add_f32 v[2:3], v[18:19], v[20:21]
	v_cvt_pk_bf16_f32 v115, v4, v5
	v_cvt_pk_bf16_f32 v116, v16, v17
	v_cvt_pk_bf16_f32 v117, v6, v7
	v_cvt_pk_bf16_f32 v118, v10, v11
	v_cvt_pk_bf16_f32 v119, v0, v1
	v_cvt_pk_bf16_f32 v120, v14, v15
	v_cvt_pk_bf16_f32 v121, v2, v3
	v_or_b32_e32 v9, 32, v237
	v_mul_u32_u24_e32 v0, 0x600, v9
	v_lshlrev_b32_e32 v0, 1, v0
	v_mov_b32_e32 v1, v97
	v_lshl_add_u64 v[0:1], s[42:43], 0, v[0:1]
	v_lshl_add_u64 v[4:5], v[0:1], 0, v[96:97]
	global_load_dwordx4 v[122:125], v[4:5], off
	global_load_dwordx4 v[126:129], v[4:5], off offset:32
	global_load_dwordx4 v[130:133], v[4:5], off offset:64
	global_load_dwordx4 v[134:137], v[4:5], off offset:96
	global_load_dwordx4 v[0:3], v[4:5], off offset:128
	s_nop 0
	global_load_dwordx4 v[4:7], v[4:5], off offset:160
	v_or_b32_e32 v9, s63, v9
	s_nop 0
	v_cvt_f32_i32_e32 v87, v9
	v_add_u32_e32 v9, s36, v8
	v_and_b32_e32 v10, 7, v8
	v_ashrrev_i32_e32 v88, 3, v9
	v_lshlrev_b32_e32 v28, 4, v10
	v_mul_f32_e32 v11, v22, v87
	v_lshl_or_b32 v96, v88, 11, v28
	v_mul_f32_e32 v12, 0.15915494, v11
	v_lshlrev_b32_e32 v89, 3, v10
	v_lshlrev_b32_e32 v66, 6, v88
	v_lshl_add_u64 v[34:35], s[10:11], 0, v[96:97]
	v_rndne_f32_e32 v12, v12
	v_or_b32_e32 v30, v66, v89
	v_mov_b32_e32 v31, v97
	v_add_co_u32_e32 v18, vcc, s39, v34
	v_fmac_f32_e32 v11, 0xc0c90fdb, v12
	v_lshl_add_u64 v[36:37], s[8:9], 0, v[30:31]
	v_addc_co_u32_e32 v19, vcc, 0, v35, vcc
	v_fmac_f32_e32 v11, 0x343bbd2e, v12
	v_lshlrev_b32_e32 v32, 4, v9
	v_mov_b32_e32 v33, v97
	v_add_co_u32_e32 v40, vcc, s92, v36
	v_mul_f32_e32 v46, 0.15915494, v11
	global_load_dwordx4 v[10:13], v96, s[10:11]
	global_load_dwordx4 v[14:17], v32, s[12:13]
	v_lshl_add_u64 v[38:39], s[12:13], 0, v[32:33]
	global_load_dwordx4 v[18:21], v[18:19], off
	v_addc_co_u32_e32 v41, vcc, 0, v37, vcc
	global_load_dwordx2 v[42:43], v30, s[8:9]
	global_load_dwordx2 v[44:45], v[40:41], off offset:-4096
	v_add_co_u32_e32 v22, vcc, s39, v38
	v_mul_f32_e32 v9, v27, v87
	s_nop 0
	v_addc_co_u32_e32 v23, vcc, 0, v39, vcc
	global_load_dwordx4 v[22:25], v[22:23], off
	v_mul_f32_e32 v27, 0.15915494, v9
	v_rndne_f32_e32 v27, v27
	v_fmac_f32_e32 v9, 0xc0c90fdb, v27
	v_fmac_f32_e32 v9, 0x343bbd2e, v27
	v_mul_f32_e32 v9, 0.15915494, v9
	v_cos_f32_e32 v48, v9
	v_sin_f32_e32 v50, v9
	v_mul_f32_e32 v9, v29, v87
	v_mul_f32_e32 v27, 0.15915494, v9
	v_rndne_f32_e32 v27, v27
	v_fmac_f32_e32 v9, 0xc0c90fdb, v27
	v_fmac_f32_e32 v9, 0x343bbd2e, v27
	v_mul_f32_e32 v9, 0.15915494, v9
	v_cos_f32_e32 v49, v9
	v_sin_f32_e32 v51, v9
	v_mul_f32_e32 v9, v47, v87
	v_mul_f32_e32 v27, 0.15915494, v9
	v_rndne_f32_e32 v27, v27
	v_fmac_f32_e32 v9, 0xc0c90fdb, v27
	v_fmac_f32_e32 v9, 0x343bbd2e, v27
	v_mul_f32_e32 v9, 0.15915494, v9
	v_cos_f32_e32 v52, v9
	v_sin_f32_e32 v54, v9
	v_mul_f32_e32 v9, v53, v87
	v_mul_f32_e32 v27, 0.15915494, v9
	v_rndne_f32_e32 v27, v27
	v_fmac_f32_e32 v9, 0xc0c90fdb, v27
	v_fmac_f32_e32 v9, 0x343bbd2e, v27
	v_mul_f32_e32 v9, 0.15915494, v9
	v_cos_f32_e32 v53, v9
	v_sin_f32_e32 v55, v9
	v_mul_f32_e32 v9, v56, v87
	v_mul_f32_e32 v27, 0.15915494, v9
	v_rndne_f32_e32 v27, v27
	v_fmac_f32_e32 v9, 0xc0c90fdb, v27
	v_fmac_f32_e32 v9, 0x343bbd2e, v27
	v_mul_f32_e32 v9, 0.15915494, v9
	v_cos_f32_e32 v56, v9
	v_sin_f32_e32 v58, v9
	v_mul_f32_e32 v9, v57, v87
	v_mul_f32_e32 v27, 0.15915494, v9
	v_rndne_f32_e32 v27, v27
	v_fmac_f32_e32 v9, 0xc0c90fdb, v27
	v_fmac_f32_e32 v9, 0x343bbd2e, v27
	v_mul_lo_u32 v29, v88, s5
	s_mov_b32 s8, 0x60000
	v_mul_f32_e32 v9, 0.15915494, v9
	v_bfe_u32 v27, v8, 5, 1
	v_add_u32_e32 v238, v29, v28
	v_add_co_u32_e32 v8, vcc, s8, v38
	v_cos_f32_e32 v57, v9
	v_sin_f32_e32 v59, v9
	v_addc_co_u32_e32 v9, vcc, 0, v39, vcc
	v_sub_u32_e32 v239, v238, v89
	v_sub_u32_e32 v240, v238, v66
	v_add_u32_e32 v47, 0, v238
	global_load_dwordx4 v[138:141], v[8:9], off
	v_add_u32_e32 v8, 0, v239
	v_add_u32_e32 v9, 0, v240
	global_load_dwordx2 v[188:189], v[40:41], off
	v_lshlrev_b32_e32 v186, 4, v27
	v_mad_u32_u24 v241, v187, s5, v186
	v_add_u32_e32 v242, 0, v241
	s_waitcnt vmcnt(9)
	v_lshlrev_b32_e32 v62, 16, v0
	v_and_b32_e32 v63, 0xffff0000, v0
	s_waitcnt vmcnt(7)
	ds_write_b128 v47, v[10:13]
	v_lshlrev_b32_e32 v60, 16, v4
	v_and_b32_e32 v61, 0xffff0000, v4
	v_pk_mul_f32 v[64:65], v[50:51], v[62:63]
	v_lshlrev_b32_e32 v0, 16, v1
	s_waitcnt vmcnt(4)
	ds_write_b64 v8, v[42:43] offset:128
	ds_write_b128 v9, v[14:17] offset:13312
	ds_write_b128 v47, v[18:21] offset:22528
	s_waitcnt vmcnt(3)
	ds_write_b64 v8, v[44:45] offset:22656
	s_waitcnt vmcnt(2)
	ds_write_b128 v9, v[22:25] offset:35840
	v_add_co_u32_e32 v8, vcc, s4, v34
	v_pk_fma_f32 v[84:85], v[48:49], v[60:61], v[64:65]
	s_nop 0
	v_addc_co_u32_e32 v9, vcc, 0, v35, vcc
	v_add_co_u32_e32 v10, vcc, s4, v38
	v_and_b32_e32 v1, 0xffff0000, v1
	s_nop 0
	v_addc_co_u32_e32 v11, vcc, 0, v39, vcc
	global_load_dwordx4 v[142:145], v[8:9], off
	global_load_dwordx4 v[146:149], v[10:11], off
	v_add_co_u32_e32 v8, vcc, s8, v34
	s_movk_i32 s8, 0x3000
	s_nop 0
	v_addc_co_u32_e32 v9, vcc, 0, v35, vcc
	global_load_dwordx4 v[150:153], v[8:9], off
	v_add_co_u32_e32 v8, vcc, s8, v36
	v_lshlrev_b32_e32 v4, 16, v5
	s_nop 0
	v_addc_co_u32_e32 v9, vcc, 0, v37, vcc
	global_load_dwordx2 v[190:191], v[8:9], off
	s_waitcnt lgkmcnt(0)
	s_barrier
; #define LAS __attribute__((address_space(3)))
; __device__ __forceinline__ unsigned pk(float lo, float hi) { f32x2_t v = {lo, hi}; bf16x2_t b = __builtin_convertvector(v, bf16x2_t); return __builtin_bit_cast(unsigned, b); }
;     ...
;             for (int j = 0; j < 8; ++j) { __builtin_amdgcn_sched_barrier(0); const float fi = hi ? invf_c(8 + j) : invf_c(j); float c, s; rope_cs(pos, fi, c, s);
;                 const float x1 = a[j], x2 = b[j]; a[j] = x1 * c - x2 * s; b[j] = x2 * c + x1 * s; }
;             u32x4 wa, wb; wa.x = pk(a[0], a[1]); wa.y = pk(a[2], a[3]); wa.z = pk(a[4], a[5]); wa.w = pk(a[6], a[7]); wb.x = pk(b[0], b[1]); wb.y = pk(b[2], b[3]); wb.z = pk(b[4], b[5]); wb.w = pk(b[6], b[7]);
;             qf[qb][ND - 2] = __builtin_bit_cast(bf16x8, wa); qf[qb][ND - 1] = __builtin_bit_cast(bf16x8, wb);
; template <int MODE, bool FAST> __device__ __forceinline__ bool attn_unit(LAS unsigned char* lds, const AttU& U, const int wv) {
;     ...
;     pb[1][0] = (bf16x8){0, 0, 0, 0, 0, 0, 0, 0}; pb[1][1] = pb[1][0];
;     ATT_QK(0, 0, 0);
;     bf16x8 kpre[NPRE > 0 ? NPRE : 1];
; #pragma unroll
;     for (int i_ = 0; i_ < NPRE; ++i_) kpre[i_] = *(LAS const bf16x8*)(lds + koff + i_ * 32);
;     ...
;     if constexpr (FAST) {
;         for (int t2 = U.kt0; t2 < U.kt1; t2 += 2) { ATT_TILE(t2, 4, rk, rr, rv); ATT_TILE(t2 + 1, 4, rk2, rr2, rv2); }
	ds_read_b128 v[80:83], v242
	ds_read_b128 v[174:177], v242 offset:32
	s_waitcnt lgkmcnt(1)
	v_mfma_f32_32x32x16_bf16 v[64:79], v[80:83], v[98:101], 0
	ds_read_b128 v[170:173], v242 offset:64
	v_and_b32_e32 v5, 0xffff0000, v5
	v_mul_f32_e64 v8, v54, v0
	v_mul_f32_e64 v9, v55, v1
	v_lshlrev_b32_e32 v18, 16, v3
	v_pk_fma_f32 v[12:13], v[52:53], v[4:5], v[8:9]
	v_pk_mul_f32 v[4:5], v[54:55], v[4:5]
	v_lshlrev_b32_e32 v8, 16, v2
	s_waitcnt lgkmcnt(1)
	v_mfma_f32_32x32x16_bf16 v[64:79], v[174:177], v[102:105], v[64:79]
	v_and_b32_e32 v9, 0xffff0000, v2
	v_fma_f32 v4, v52, v0, -v4
	v_fma_f32 v5, v53, v1, -v5
	v_lshlrev_b32_e32 v0, 16, v6
	v_and_b32_e32 v1, 0xffff0000, v6
	v_pk_mul_f32 v[10:11], v[58:59], v[8:9]
	v_and_b32_e32 v19, 0xffff0000, v3
	v_pk_fma_f32 v[14:15], v[56:57], v[0:1], v[10:11]
	v_pk_mul_f32 v[0:1], v[58:59], v[0:1]
	v_cos_f32_e32 v26, v46
	v_pk_fma_f32 v[16:17], v[56:57], v[8:9], v[0:1] neg_lo:[0,0,1] neg_hi:[0,0,1]
	ds_read_b128 v[8:11], v242 offset:96
	s_waitcnt lgkmcnt(1)
	v_mfma_f32_32x32x16_bf16 v[64:79], v[170:173], v[106:109], v[64:79]
	v_mul_f32_e32 v0, v86, v87
	v_mul_f32_e32 v1, 0.15915494, v0
	v_rndne_f32_e32 v1, v1
	v_fmac_f32_e32 v0, 0xc0c90fdb, v1
	v_fmac_f32_e32 v0, 0x343bbd2e, v1
	v_mul_f32_e32 v0, 0.15915494, v0
	v_sin_f32_e32 v47, v0
	v_cos_f32_e32 v27, v0
	ds_read_b128 v[0:3], v242 offset:128
	s_waitcnt lgkmcnt(1)
	v_mfma_f32_32x32x16_bf16 v[64:79], v[8:11], v[110:113], v[64:79]
	v_sin_f32_e32 v46, v46
	v_lshlrev_b32_e32 v6, 16, v7
	v_and_b32_e32 v7, 0xffff0000, v7
	v_cvt_pk_bf16_f32 v155, v4, v5
	v_pk_mul_f32 v[8:9], v[46:47], v[18:19]
	v_pk_mul_f32 v[50:51], v[50:51], v[60:61]
	v_pk_fma_f32 v[8:9], v[26:27], v[6:7], v[8:9]
	v_pk_mul_f32 v[6:7], v[46:47], v[6:7]
	v_pk_fma_f32 v[48:49], v[48:49], v[62:63], v[50:51] neg_lo:[0,0,1] neg_hi:[0,0,1]
	v_pk_fma_f32 v[10:11], v[26:27], v[18:19], v[6:7] neg_lo:[0,0,1] neg_hi:[0,0,1]
	ds_read_b128 v[4:7], v242 offset:160
	s_waitcnt lgkmcnt(1)
	v_mfma_f32_32x32x16_bf16 v[64:79], v[0:3], v[114:117], v[64:79]
	v_lshlrev_b32_e32 v0, 6, v187
	s_add_u32 s6, s56, s6
	v_cvt_pk_bf16_f32 v154, v48, v49
	v_sub_u32_e32 v243, v241, v0
	s_addc_u32 s7, s57, s7
	v_mov_b32_e32 v48, 0
	v_cvt_pk_bf16_f32 v156, v16, v17
	s_waitcnt lgkmcnt(0)
	v_mfma_f32_32x32x16_bf16 v[64:79], v[4:7], v[118:121], v[64:79]
	v_cvt_pk_bf16_f32 v157, v10, v11
	v_cvt_pk_bf16_f32 v158, v84, v85
	v_cvt_pk_bf16_f32 v159, v12, v13
	v_cvt_pk_bf16_f32 v160, v14, v15
	v_cvt_pk_bf16_f32 v161, v8, v9
	v_add_u32_e32 v244, 0, v243
	v_add_u32_e32 v245, v89, v29
	v_mad_u64_u32 v[198:199], s[8:9], v88, s69, v[28:29]
	v_lshl_or_b32 v96, s44, 7, v96
	v_mov_b32_e32 v200, v32
	s_add_u32 s98, s40, 0x12380000
	s_addc_u32 s99, s41, 0
	s_add_u32 s100, s40, s30
	s_addc_u32 s101, s41, s31
	s_add_u32 s100, s100, 0x18380000
	s_addc_u32 s101, s101, 0
	v_lshl_add_u64 v[202:203], s[6:7], 0, v[30:31]
	s_mov_b64 s[42:43], 0
	v_mov_b32_e32 v162, 0
	v_mov_b32_e32 v163, 0
	v_mov_b32_e32 v164, 0
	v_mov_b32_e32 v165, 0
	v_mov_b32_e32 v166, 0
	v_mov_b32_e32 v167, 0
	v_mov_b32_e32 v168, 0
	v_mov_b32_e32 v169, 0
	s_mov_b32 s61, 0
	v_mov_b32_e32 v49, v48
	v_mov_b32_e32 v50, v48
	v_mov_b32_e32 v51, v48
	v_mov_b32_e32 v52, v48
	v_mov_b32_e32 v53, v48
	v_mov_b32_e32 v54, v48
	v_mov_b32_e32 v55, v48
	v_mov_b32_e32 v56, v48
	v_mov_b32_e32 v57, v48
	v_mov_b32_e32 v58, v48
	v_mov_b32_e32 v59, v48
	v_mov_b32_e32 v60, v48
	v_mov_b32_e32 v61, v48
	v_mov_b32_e32 v62, v48
	v_mov_b32_e32 v63, v48
	v_mov_b32_e32 v32, v48
	v_mov_b32_e32 v33, v48
	v_mov_b32_e32 v34, v48
	v_mov_b32_e32 v35, v48
	v_mov_b32_e32 v36, v48
	v_mov_b32_e32 v37, v48
	v_mov_b32_e32 v38, v48
	v_mov_b32_e32 v39, v48
	v_mov_b32_e32 v40, v48
	v_mov_b32_e32 v41, v48
	v_mov_b32_e32 v42, v48
	v_mov_b32_e32 v43, v48
	v_mov_b32_e32 v44, v48
	v_mov_b32_e32 v45, v48
	v_mov_b32_e32 v46, v48
	v_mov_b32_e32 v47, v48
	v_mov_b32_e32 v16, v48
	v_mov_b32_e32 v17, v48
	v_mov_b32_e32 v18, v48
	v_mov_b32_e32 v19, v48
	v_mov_b32_e32 v20, v48
	v_mov_b32_e32 v21, v48
	v_mov_b32_e32 v22, v48
	v_mov_b32_e32 v23, v48
	v_mov_b32_e32 v24, v48
	v_mov_b32_e32 v25, v48
	v_mov_b32_e32 v26, v48
	v_mov_b32_e32 v27, v48
	v_mov_b32_e32 v28, v48
	v_mov_b32_e32 v29, v48
	v_mov_b32_e32 v30, v48
	v_mov_b32_e32 v31, v48
	v_mov_b32_e32 v0, v48
	v_mov_b32_e32 v1, v48
	v_mov_b32_e32 v2, v48
	v_mov_b32_e32 v3, v48
	v_mov_b32_e32 v4, v48
	v_mov_b32_e32 v5, v48
	v_mov_b32_e32 v6, v48
	v_mov_b32_e32 v7, v48
	v_mov_b32_e32 v8, v48
	v_mov_b32_e32 v9, v48
	v_mov_b32_e32 v10, v48
	v_mov_b32_e32 v11, v48
	v_mov_b32_e32 v12, v48
	v_mov_b32_e32 v13, v48
	v_mov_b32_e32 v14, v48
	v_mov_b32_e32 v15, v48
	v_mov_b32_e32 v204, v48
	v_mov_b32_e32 v205, v48
	.p2align 6
